# accumulator zeroing removed: first K-loop iteration peeled with C=0 operand; duplicate zero block deleted
# speedup vs baseline: 1.1000x; 1.0194x over previous
; #define PG8_STAGE(bufoff, gbase, voff) do { _Pragma("unroll") for (int _i = 0; _i < 2; ++_i) \
;         __builtin_amdgcn_global_load_lds((const unsigned*)((const char*)(gbase) + (voff)[_i]), (PG8_LAS unsigned*)(lds + (bufoff) + ldsw + _i * 8192), 16, 0, 0); } while (0)
; #define PG8_LDA(dst, b, h) do { _Pragma("unroll") for (int m = 0; m < 4; ++m) _Pragma("unroll") for (int k = 0; k < 2; ++k) dst[m][k] = *(const PG8_LAS bf16x8*)(lds + PG8_SA(b, h) + aoff + m * 2048 + k * 1024); } while (0)
; #define PG8_LDB(dst, b, h) do { _Pragma("unroll") for (int n = 0; n < 2; ++n) _Pragma("unroll") for (int k = 0; k < 2; ++k) dst[n][k] = *(const PG8_LAS bf16x8*)(lds + PG8_SB(b, h) + boff + n * 2048 + k * 1024); } while (0)
; #define PG8_MMA(ai, bj, At, Bt) do { __builtin_amdgcn_s_setprio(1); _Pragma("unroll") for (int m = 0; m < 4; ++m) _Pragma("unroll") for (int n = 0; n < 2; ++n) _Pragma("unroll") for (int k = 0; k < 2; ++k) \
;         acc[ai][bj][m][n] = __builtin_amdgcn_mfma_f32_16x16x32_bf16(Bt[n][k], At[m][k], acc[ai][bj][m][n], 0, 0, 0); __builtin_amdgcn_s_setprio(0); } while (0)
; #define PG8_WAIT_V(n) asm volatile("s_waitcnt vmcnt(" #n ")" ::: "memory")
;     ...
;         const bool has_next = S.next(ui + 1, nxt);
;         const char* nA = has_next ? (const char*)gA + (size_t)nxt.pm * tstepA + (size_t)nxt.pn * acolB : cA; const char* nB = has_next ? (const char*)gB + (size_t)nxt.pn * tstepB : cB;
;         for (int t = 0; t < nt; t += 2) {
;             const bool last = (t == nt - 2);
;             const char* a1 = cA + (size_t)(t + 1) * kstep;
;             const char* a2 = last ? nA : cA + (size_t)(t + 2) * kstep; const char* b2 = last ? nB : cB + (size_t)(t + 2) * kstep;
;             const char* a3 = a2 + kstep; const char* b3 = b2 + kstep;
;             if (last && has_next) S.a_ready(nxt);
;             if constexpr (SP2) {
;             PG8_LDB(B0, 0, 0); PG8_LDB(B1, 0, 1); PG8_SCHED; PG8_LDA(At, 0, 0); PG8_STAGE(PG8_SA(1, 1), a1 + hstepA, voffA);
;             PG8_WAIT_V(8); PG8_WAIT_L(0); PG8_BAR; PG8_MMA(0, 0, At, B0); PG8_MMA(0, 1, At, B1); PG8_BAR; PG8_SCHED;
;             PG8_LDA(At, 0, 1); PG8_STAGE(PG8_SB(0, 0), b2, voffB); PG8_STAGE(PG8_SB(0, 1), b2 + hstepB, voffB); PG8_STAGE(PG8_SA(0, 0), a2, voffA);
;             PG8_WAIT_V(8); PG8_WAIT_L(0); PG8_BAR; PG8_MMA(1, 0, At, B0); PG8_MMA(1, 1, At, B1); PG8_BAR; PG8_SCHED;
.LBB0_127:
	s_ashr_i32 s91, s90, 31
	s_lshl_b64 s[10:11], s[90:91], 19
	s_add_u32 s22, s44, s10
	s_addc_u32 s23, s45, s11
	s_lshl_b64 s[10:11], s[88:89], 9
	s_add_u32 s94, s22, s10
	s_addc_u32 s95, s23, s11
	s_andn2_b64 vcc, exec, s[72:73]
	s_cbranch_vccnz .LBB0_130
	s_and_b64 s[10:11], s[40:41], exec
	s_cselect_b32 s10, s95, s9
	s_cselect_b32 s11, s94, s8
	s_add_u32 s22, s6, 0x100
	s_addc_u32 s23, s7, 0
	s_add_u32 s6, s8, 0x40080
	s_addc_u32 s7, s9, 0
	s_mov_b32 s8, 0
	s_add_i32 s24, s8, 2
	s_add_u32 s25, s6, 0xfffc0080
	s_addc_u32 s9, s7, -1
	s_add_i32 s27, 0, 0x10000
	s_cmp_eq_u32 s18, s8
	s_cselect_b32 s9, s10, s9
	s_cselect_b32 s8, s11, s25
	v_add_u32_e32 v152, s27, v159
	s_cselect_b32 s35, s93, s23
	s_cselect_b32 s34, s92, s22
	s_add_i32 s25, 0, 0x14000
	ds_read_b128 v[144:147], v152
	ds_read_b128 v[148:151], v152 offset:1024
	ds_read_b128 v[154:157], v152 offset:2048
	ds_read_b128 v[160:163], v152 offset:3072
	v_add_u32_e32 v152, s25, v159
	ds_read_b128 v[172:175], v152
	ds_read_b128 v[180:183], v152 offset:1024
	ds_read_b128 v[184:187], v152 offset:2048
	ds_read_b128 v[188:191], v152 offset:3072
	v_lshl_add_u64 v[164:165], s[6:7], 0, v[142:143]
	s_add_i32 m0, s2, 0xc000
	ds_read_b128 v[192:195], v179
	ds_read_b128 v[196:199], v179 offset:1024
	ds_read_b128 v[200:203], v179 offset:2048
	ds_read_b128 v[204:207], v179 offset:3072
	ds_read_b128 v[208:211], v179 offset:4096
	ds_read_b128 v[212:215], v179 offset:5120
	ds_read_b128 v[216:219], v179 offset:6144
	ds_read_b128 v[220:223], v179 offset:7168
	global_load_lds_dwordx4 v[164:165], off
	v_lshl_add_u64 v[164:165], s[6:7], 0, v[140:141]
	s_add_i32 m0, s2, 0xe000
	s_nop 0
	global_load_lds_dwordx4 v[164:165], off
	s_waitcnt vmcnt(8)
	s_waitcnt lgkmcnt(0)
	s_barrier
	s_setprio 1
	s_waitcnt lgkmcnt(0)
	v_mfma_f32_16x16x32_bf16 v[126:129], v[144:147], v[192:195], 0
	v_mfma_f32_16x16x32_bf16 v[122:125], v[154:157], v[192:195], 0
	v_mfma_f32_16x16x32_bf16 v[110:113], v[144:147], v[200:203], 0
	v_mfma_f32_16x16x32_bf16 v[106:109], v[154:157], v[200:203], 0
	v_mfma_f32_16x16x32_bf16 v[94:97], v[144:147], v[208:211], 0
	v_mfma_f32_16x16x32_bf16 v[90:93], v[154:157], v[208:211], 0
	v_mfma_f32_16x16x32_bf16 v[78:81], v[144:147], v[216:219], 0
	v_mfma_f32_16x16x32_bf16 v[74:77], v[154:157], v[216:219], 0
	v_mfma_f32_16x16x32_bf16 v[126:129], v[148:151], v[196:199], v[126:129]
	v_mfma_f32_16x16x32_bf16 v[122:125], v[160:163], v[196:199], v[122:125]
	v_mfma_f32_16x16x32_bf16 v[110:113], v[148:151], v[204:207], v[110:113]
	v_mfma_f32_16x16x32_bf16 v[106:109], v[160:163], v[204:207], v[106:109]
	v_mfma_f32_16x16x32_bf16 v[94:97], v[148:151], v[212:215], v[94:97]
	v_mfma_f32_16x16x32_bf16 v[90:93], v[160:163], v[212:215], v[90:93]
	v_mfma_f32_16x16x32_bf16 v[78:81], v[148:151], v[220:223], v[78:81]
	v_mfma_f32_16x16x32_bf16 v[74:77], v[160:163], v[220:223], v[74:77]
	s_setprio 0
	s_setprio 1
	v_mfma_f32_16x16x32_bf16 v[118:121], v[172:175], v[192:195], 0
	v_mfma_f32_16x16x32_bf16 v[114:117], v[184:187], v[192:195], 0
	v_mfma_f32_16x16x32_bf16 v[102:105], v[172:175], v[200:203], 0
	v_mfma_f32_16x16x32_bf16 v[98:101], v[184:187], v[200:203], 0
	v_mfma_f32_16x16x32_bf16 v[86:89], v[172:175], v[208:211], 0
	v_mfma_f32_16x16x32_bf16 v[82:85], v[184:187], v[208:211], 0
	v_mfma_f32_16x16x32_bf16 v[70:73], v[172:175], v[216:219], 0
	v_mfma_f32_16x16x32_bf16 v[66:69], v[184:187], v[216:219], 0
	v_mfma_f32_16x16x32_bf16 v[118:121], v[180:183], v[196:199], v[118:121]
	v_mfma_f32_16x16x32_bf16 v[114:117], v[188:191], v[196:199], v[114:117]
	v_mfma_f32_16x16x32_bf16 v[102:105], v[180:183], v[204:207], v[102:105]
	v_mfma_f32_16x16x32_bf16 v[98:101], v[188:191], v[204:207], v[98:101]
	v_mfma_f32_16x16x32_bf16 v[86:89], v[180:183], v[212:215], v[86:89]
	v_mfma_f32_16x16x32_bf16 v[82:85], v[188:191], v[212:215], v[82:85]
	v_mfma_f32_16x16x32_bf16 v[70:73], v[180:183], v[220:223], v[70:73]
	v_mfma_f32_16x16x32_bf16 v[66:69], v[188:191], v[220:223], v[66:69]
	s_setprio 0
	s_barrier
	s_add_i32 s27, s27, s0
	v_lshl_add_u64 v[164:165], s[34:35], 0, v[134:135]
	s_mov_b32 m0, s27
	ds_read_b128 v[192:195], v179 offset:16384
	ds_read_b128 v[196:199], v179 offset:17408
	ds_read_b128 v[200:203], v179 offset:18432
	ds_read_b128 v[204:207], v179 offset:19456
	ds_read_b128 v[208:211], v179 offset:20480
	ds_read_b128 v[212:215], v179 offset:21504
	ds_read_b128 v[216:219], v179 offset:22528
	ds_read_b128 v[220:223], v179 offset:23552
	global_load_lds_dwordx4 v[164:165], off
	s_add_i32 m0, s27, 0x2000
	v_lshl_add_u64 v[168:169], s[34:35], 0, v[130:131]
	s_add_u32 s34, s34, s42
	s_addc_u32 s35, s35, s43
	s_add_i32 s25, s25, s0
	global_load_lds_dwordx4 v[168:169], off
	v_lshl_add_u64 v[170:171], s[34:35], 0, v[134:135]
	s_mov_b32 m0, s25
	v_lshl_add_u64 v[176:177], s[34:35], 0, v[130:131]
	global_load_lds_dwordx4 v[170:171], off
	s_add_i32 m0, s25, 0x2000
	v_lshl_add_u64 v[224:225], s[8:9], 0, v[136:137]
	global_load_lds_dwordx4 v[176:177], off
	s_mov_b32 m0, s2
	v_lshl_add_u64 v[226:227], s[8:9], 0, v[132:133]
	global_load_lds_dwordx4 v[224:225], off
	s_mov_b32 m0, s3
	s_nop 0
	global_load_lds_dwordx4 v[226:227], off
	s_waitcnt vmcnt(8)
	s_waitcnt lgkmcnt(0)
	s_barrier
; #define PG8_STAGE(bufoff, gbase, voff) do { _Pragma("unroll") for (int _i = 0; _i < 2; ++_i) \
;         __builtin_amdgcn_global_load_lds((const unsigned*)((const char*)(gbase) + (voff)[_i]), (PG8_LAS unsigned*)(lds + (bufoff) + ldsw + _i * 8192), 16, 0, 0); } while (0)
; #define PG8_LDA(dst, b, h) do { _Pragma("unroll") for (int m = 0; m < 4; ++m) _Pragma("unroll") for (int k = 0; k < 2; ++k) dst[m][k] = *(const PG8_LAS bf16x8*)(lds + PG8_SA(b, h) + aoff + m * 2048 + k * 1024); } while (0)
; #define PG8_LDB(dst, b, h) do { _Pragma("unroll") for (int n = 0; n < 2; ++n) _Pragma("unroll") for (int k = 0; k < 2; ++k) dst[n][k] = *(const PG8_LAS bf16x8*)(lds + PG8_SB(b, h) + boff + n * 2048 + k * 1024); } while (0)
; #define PG8_MMA(ai, bj, At, Bt) do { __builtin_amdgcn_s_setprio(1); _Pragma("unroll") for (int m = 0; m < 4; ++m) _Pragma("unroll") for (int n = 0; n < 2; ++n) _Pragma("unroll") for (int k = 0; k < 2; ++k) \
;         acc[ai][bj][m][n] = __builtin_amdgcn_mfma_f32_16x16x32_bf16(Bt[n][k], At[m][k], acc[ai][bj][m][n], 0, 0, 0); __builtin_amdgcn_s_setprio(0); } while (0)
; #define PG8_WAIT_V(n) asm volatile("s_waitcnt vmcnt(" #n ")" ::: "memory")
; #define PG8_WAIT_L(n) asm volatile("s_waitcnt lgkmcnt(" #n ")" ::: "memory")
; #define PG8_BAR __builtin_amdgcn_s_barrier()
; #define PG8_SCHED __builtin_amdgcn_sched_barrier(0)
;     ...
;             PG8_WAIT_V(8); PG8_WAIT_L(0); PG8_BAR; PG8_MMA(1, 0, At, B0); PG8_MMA(1, 1, At, B1); PG8_BAR; PG8_SCHED;
;             PG8_LDB(B0, 1, 0); PG8_LDB(B1, 1, 1); PG8_SCHED; PG8_LDA(At, 1, 0); PG8_STAGE(PG8_SA(0, 1), a2 + hstepA, voffA);
;             PG8_WAIT_V(8); PG8_WAIT_L(0); PG8_BAR; PG8_MMA(0, 0, At, B0); PG8_MMA(0, 1, At, B1); PG8_BAR; PG8_SCHED;
	s_setprio 1
	s_waitcnt lgkmcnt(0)
	v_mfma_f32_16x16x32_bf16 v[62:65], v[144:147], v[192:195], 0
	v_mfma_f32_16x16x32_bf16 v[58:61], v[154:157], v[192:195], 0
	v_mfma_f32_16x16x32_bf16 v[46:49], v[144:147], v[200:203], 0
	v_mfma_f32_16x16x32_bf16 v[42:45], v[154:157], v[200:203], 0
	v_mfma_f32_16x16x32_bf16 v[30:33], v[144:147], v[208:211], 0
	v_mfma_f32_16x16x32_bf16 v[26:29], v[154:157], v[208:211], 0
	v_mfma_f32_16x16x32_bf16 v[14:17], v[144:147], v[216:219], 0
	v_mfma_f32_16x16x32_bf16 v[10:13], v[154:157], v[216:219], 0
	v_mfma_f32_16x16x32_bf16 v[62:65], v[148:151], v[196:199], v[62:65]
	v_mfma_f32_16x16x32_bf16 v[58:61], v[160:163], v[196:199], v[58:61]
	v_mfma_f32_16x16x32_bf16 v[46:49], v[148:151], v[204:207], v[46:49]
	v_mfma_f32_16x16x32_bf16 v[42:45], v[160:163], v[204:207], v[42:45]
	v_mfma_f32_16x16x32_bf16 v[30:33], v[148:151], v[212:215], v[30:33]
	v_mfma_f32_16x16x32_bf16 v[26:29], v[160:163], v[212:215], v[26:29]
	v_mfma_f32_16x16x32_bf16 v[14:17], v[148:151], v[220:223], v[14:17]
	v_mfma_f32_16x16x32_bf16 v[10:13], v[160:163], v[220:223], v[10:13]
	s_setprio 0
	s_setprio 1
	v_mfma_f32_16x16x32_bf16 v[54:57], v[172:175], v[192:195], 0
	v_mfma_f32_16x16x32_bf16 v[50:53], v[184:187], v[192:195], 0
	v_mfma_f32_16x16x32_bf16 v[38:41], v[172:175], v[200:203], 0
	v_mfma_f32_16x16x32_bf16 v[34:37], v[184:187], v[200:203], 0
	v_mfma_f32_16x16x32_bf16 v[22:25], v[172:175], v[208:211], 0
	v_mfma_f32_16x16x32_bf16 v[18:21], v[184:187], v[208:211], 0
	v_mfma_f32_16x16x32_bf16 v[6:9], v[172:175], v[216:219], 0
	v_mfma_f32_16x16x32_bf16 v[2:5], v[184:187], v[216:219], 0
	v_mfma_f32_16x16x32_bf16 v[54:57], v[180:183], v[196:199], v[54:57]
	v_mfma_f32_16x16x32_bf16 v[50:53], v[188:191], v[196:199], v[50:53]
	v_mfma_f32_16x16x32_bf16 v[38:41], v[180:183], v[204:207], v[38:41]
	v_mfma_f32_16x16x32_bf16 v[34:37], v[188:191], v[204:207], v[34:37]
	v_mfma_f32_16x16x32_bf16 v[22:25], v[180:183], v[212:215], v[22:25]
	v_mfma_f32_16x16x32_bf16 v[18:21], v[188:191], v[212:215], v[18:21]
	v_mfma_f32_16x16x32_bf16 v[6:9], v[180:183], v[220:223], v[6:9]
	v_mfma_f32_16x16x32_bf16 v[2:5], v[188:191], v[220:223], v[2:5]
	s_setprio 0
	s_barrier
	s_add_i32 s25, 0, 0x18000
	v_add_u32_e32 v152, s25, v159
	s_add_i32 s27, 0, 0x1c000
	ds_read_b128 v[144:147], v152
	ds_read_b128 v[148:151], v152 offset:1024
	ds_read_b128 v[154:157], v152 offset:2048
	ds_read_b128 v[160:163], v152 offset:3072
	v_add_u32_e32 v152, s27, v159
	ds_read_b128 v[172:175], v152
	ds_read_b128 v[180:183], v152 offset:1024
	ds_read_b128 v[184:187], v152 offset:2048
	ds_read_b128 v[188:191], v152 offset:3072
	s_add_u32 s8, s8, 0x40000
	s_addc_u32 s9, s9, 0
	s_mov_b32 m0, s12
	v_lshl_add_u64 v[228:229], s[8:9], 0, v[136:137]
	ds_read_b128 v[192:195], v179 offset:32768
	ds_read_b128 v[196:199], v179 offset:33792
	ds_read_b128 v[200:203], v179 offset:34816
	ds_read_b128 v[204:207], v179 offset:35840
	ds_read_b128 v[208:211], v179 offset:36864
	ds_read_b128 v[212:215], v179 offset:37888
	ds_read_b128 v[216:219], v179 offset:38912
	ds_read_b128 v[220:223], v179 offset:39936
	global_load_lds_dwordx4 v[228:229], off
	v_lshl_add_u64 v[228:229], s[8:9], 0, v[132:133]
	s_mov_b32 m0, s13
	s_nop 0
	global_load_lds_dwordx4 v[228:229], off
	s_waitcnt vmcnt(8)
	s_waitcnt lgkmcnt(0)
	s_barrier
	s_setprio 1
	s_waitcnt lgkmcnt(0)
	v_mfma_f32_16x16x32_bf16 v[126:129], v[144:147], v[192:195], v[126:129]
	v_mfma_f32_16x16x32_bf16 v[122:125], v[154:157], v[192:195], v[122:125]
	v_mfma_f32_16x16x32_bf16 v[110:113], v[144:147], v[200:203], v[110:113]
	v_mfma_f32_16x16x32_bf16 v[106:109], v[154:157], v[200:203], v[106:109]
	v_mfma_f32_16x16x32_bf16 v[94:97], v[144:147], v[208:211], v[94:97]
	v_mfma_f32_16x16x32_bf16 v[90:93], v[154:157], v[208:211], v[90:93]
	v_mfma_f32_16x16x32_bf16 v[78:81], v[144:147], v[216:219], v[78:81]
	v_mfma_f32_16x16x32_bf16 v[74:77], v[154:157], v[216:219], v[74:77]
	v_mfma_f32_16x16x32_bf16 v[126:129], v[148:151], v[196:199], v[126:129]
	v_mfma_f32_16x16x32_bf16 v[122:125], v[160:163], v[196:199], v[122:125]
	v_mfma_f32_16x16x32_bf16 v[110:113], v[148:151], v[204:207], v[110:113]
	v_mfma_f32_16x16x32_bf16 v[106:109], v[160:163], v[204:207], v[106:109]
	v_mfma_f32_16x16x32_bf16 v[94:97], v[148:151], v[212:215], v[94:97]
	v_mfma_f32_16x16x32_bf16 v[90:93], v[160:163], v[212:215], v[90:93]
	v_mfma_f32_16x16x32_bf16 v[78:81], v[148:151], v[220:223], v[78:81]
	v_mfma_f32_16x16x32_bf16 v[74:77], v[160:163], v[220:223], v[74:77]
	s_setprio 0
	s_setprio 1
	v_mfma_f32_16x16x32_bf16 v[118:121], v[172:175], v[192:195], v[118:121]
	v_mfma_f32_16x16x32_bf16 v[114:117], v[184:187], v[192:195], v[114:117]
	v_mfma_f32_16x16x32_bf16 v[102:105], v[172:175], v[200:203], v[102:105]
	v_mfma_f32_16x16x32_bf16 v[98:101], v[184:187], v[200:203], v[98:101]
	v_mfma_f32_16x16x32_bf16 v[86:89], v[172:175], v[208:211], v[86:89]
	v_mfma_f32_16x16x32_bf16 v[82:85], v[184:187], v[208:211], v[82:85]
	v_mfma_f32_16x16x32_bf16 v[70:73], v[172:175], v[216:219], v[70:73]
	v_mfma_f32_16x16x32_bf16 v[66:69], v[184:187], v[216:219], v[66:69]
	v_mfma_f32_16x16x32_bf16 v[118:121], v[180:183], v[196:199], v[118:121]
	v_mfma_f32_16x16x32_bf16 v[114:117], v[188:191], v[196:199], v[114:117]
	v_mfma_f32_16x16x32_bf16 v[102:105], v[180:183], v[204:207], v[102:105]
	v_mfma_f32_16x16x32_bf16 v[98:101], v[188:191], v[204:207], v[98:101]
	v_mfma_f32_16x16x32_bf16 v[86:89], v[180:183], v[212:215], v[86:89]
	v_mfma_f32_16x16x32_bf16 v[82:85], v[188:191], v[212:215], v[82:85]
	v_mfma_f32_16x16x32_bf16 v[70:73], v[180:183], v[220:223], v[70:73]
	v_mfma_f32_16x16x32_bf16 v[66:69], v[188:191], v[220:223], v[66:69]
	s_setprio 0
	s_barrier
; #define PG8_STAGE(bufoff, gbase, voff) do { _Pragma("unroll") for (int _i = 0; _i < 2; ++_i) \
;         __builtin_amdgcn_global_load_lds((const unsigned*)((const char*)(gbase) + (voff)[_i]), (PG8_LAS unsigned*)(lds + (bufoff) + ldsw + _i * 8192), 16, 0, 0); } while (0)
; #define PG8_LDA(dst, b, h) do { _Pragma("unroll") for (int m = 0; m < 4; ++m) _Pragma("unroll") for (int k = 0; k < 2; ++k) dst[m][k] = *(const PG8_LAS bf16x8*)(lds + PG8_SA(b, h) + aoff + m * 2048 + k * 1024); } while (0)
; #define PG8_MMA(ai, bj, At, Bt) do { __builtin_amdgcn_s_setprio(1); _Pragma("unroll") for (int m = 0; m < 4; ++m) _Pragma("unroll") for (int n = 0; n < 2; ++n) _Pragma("unroll") for (int k = 0; k < 2; ++k) \
;         acc[ai][bj][m][n] = __builtin_amdgcn_mfma_f32_16x16x32_bf16(Bt[n][k], At[m][k], acc[ai][bj][m][n], 0, 0, 0); __builtin_amdgcn_s_setprio(0); } while (0)
; #define PG8_WAIT_V(n) asm volatile("s_waitcnt vmcnt(" #n ")" ::: "memory")
; #define PG8_WAIT_L(n) asm volatile("s_waitcnt lgkmcnt(" #n ")" ::: "memory")
; #define PG8_BAR __builtin_amdgcn_s_barrier()
; #define PG8_SCHED __builtin_amdgcn_sched_barrier(0)
;     ...
;             PG8_LDA(At, 1, 1); PG8_STAGE(PG8_SB(1, 0), b3, voffB); PG8_STAGE(PG8_SB(1, 1), b3 + hstepB, voffB); PG8_STAGE(PG8_SA(1, 0), a3, voffA);
;             PG8_WAIT_V(8); PG8_WAIT_L(0); PG8_BAR; PG8_MMA(1, 0, At, B0); PG8_MMA(1, 1, At, B1); PG8_BAR; PG8_SCHED;
	s_add_i32 s8, s25, s0
	v_lshl_add_u64 v[164:165], v[164:165], 0, s[62:63]
	s_mov_b32 m0, s8
	ds_read_b128 v[192:195], v179 offset:49152
	ds_read_b128 v[196:199], v179 offset:50176
	ds_read_b128 v[200:203], v179 offset:51200
	ds_read_b128 v[204:207], v179 offset:52224
	ds_read_b128 v[208:211], v179 offset:53248
	ds_read_b128 v[212:215], v179 offset:54272
	ds_read_b128 v[216:219], v179 offset:55296
	ds_read_b128 v[220:223], v179 offset:56320
	global_load_lds_dwordx4 v[164:165], off
	v_lshl_add_u64 v[164:165], v[168:169], 0, s[62:63]
	s_add_i32 m0, s8, 0x2000
	s_add_i32 s8, s27, s0
	global_load_lds_dwordx4 v[164:165], off
	v_lshl_add_u64 v[164:165], v[170:171], 0, s[62:63]
	s_mov_b32 m0, s8
	s_nop 0
	global_load_lds_dwordx4 v[164:165], off
	v_lshl_add_u64 v[164:165], v[176:177], 0, s[62:63]
	s_add_i32 m0, s8, 0x2000
	s_nop 0
	global_load_lds_dwordx4 v[164:165], off
	v_lshl_add_u64 v[164:165], v[224:225], 0, s[62:63]
	s_mov_b32 m0, s16
	s_nop 0
	global_load_lds_dwordx4 v[164:165], off
	v_lshl_add_u64 v[164:165], v[226:227], 0, s[62:63]
	s_mov_b32 m0, s17
	s_nop 0
	global_load_lds_dwordx4 v[164:165], off
	s_waitcnt vmcnt(8)
	s_waitcnt lgkmcnt(0)
	s_barrier
	s_setprio 1
	s_waitcnt lgkmcnt(0)
	v_mfma_f32_16x16x32_bf16 v[62:65], v[144:147], v[192:195], v[62:65]
	v_mfma_f32_16x16x32_bf16 v[58:61], v[154:157], v[192:195], v[58:61]
	v_mfma_f32_16x16x32_bf16 v[46:49], v[144:147], v[200:203], v[46:49]
	v_mfma_f32_16x16x32_bf16 v[42:45], v[154:157], v[200:203], v[42:45]
	v_mfma_f32_16x16x32_bf16 v[30:33], v[144:147], v[208:211], v[30:33]
	v_mfma_f32_16x16x32_bf16 v[26:29], v[154:157], v[208:211], v[26:29]
	v_mfma_f32_16x16x32_bf16 v[14:17], v[144:147], v[216:219], v[14:17]
	v_mfma_f32_16x16x32_bf16 v[10:13], v[154:157], v[216:219], v[10:13]
	v_mfma_f32_16x16x32_bf16 v[62:65], v[148:151], v[196:199], v[62:65]
	v_mfma_f32_16x16x32_bf16 v[58:61], v[160:163], v[196:199], v[58:61]
	v_mfma_f32_16x16x32_bf16 v[46:49], v[148:151], v[204:207], v[46:49]
	v_mfma_f32_16x16x32_bf16 v[42:45], v[160:163], v[204:207], v[42:45]
	v_mfma_f32_16x16x32_bf16 v[30:33], v[148:151], v[212:215], v[30:33]
	v_mfma_f32_16x16x32_bf16 v[26:29], v[160:163], v[212:215], v[26:29]
	v_mfma_f32_16x16x32_bf16 v[14:17], v[148:151], v[220:223], v[14:17]
	v_mfma_f32_16x16x32_bf16 v[10:13], v[160:163], v[220:223], v[10:13]
	s_setprio 0
	s_setprio 1
	v_mfma_f32_16x16x32_bf16 v[54:57], v[172:175], v[192:195], v[54:57]
	v_mfma_f32_16x16x32_bf16 v[50:53], v[184:187], v[192:195], v[50:53]
	v_mfma_f32_16x16x32_bf16 v[38:41], v[172:175], v[200:203], v[38:41]
	v_mfma_f32_16x16x32_bf16 v[34:37], v[184:187], v[200:203], v[34:37]
	v_mfma_f32_16x16x32_bf16 v[22:25], v[172:175], v[208:211], v[22:25]
	v_mfma_f32_16x16x32_bf16 v[18:21], v[184:187], v[208:211], v[18:21]
	v_mfma_f32_16x16x32_bf16 v[6:9], v[172:175], v[216:219], v[6:9]
	v_mfma_f32_16x16x32_bf16 v[2:5], v[184:187], v[216:219], v[2:5]
	v_mfma_f32_16x16x32_bf16 v[54:57], v[180:183], v[196:199], v[54:57]
	v_mfma_f32_16x16x32_bf16 v[50:53], v[188:191], v[196:199], v[50:53]
	v_mfma_f32_16x16x32_bf16 v[38:41], v[180:183], v[204:207], v[38:41]
	v_mfma_f32_16x16x32_bf16 v[34:37], v[188:191], v[204:207], v[34:37]
	v_mfma_f32_16x16x32_bf16 v[22:25], v[180:183], v[212:215], v[22:25]
	v_mfma_f32_16x16x32_bf16 v[18:21], v[188:191], v[212:215], v[18:21]
	v_mfma_f32_16x16x32_bf16 v[6:9], v[180:183], v[220:223], v[6:9]
	v_mfma_f32_16x16x32_bf16 v[2:5], v[188:191], v[220:223], v[2:5]
	s_setprio 0
	s_barrier
	s_add_u32 s22, s22, 0x100
	s_addc_u32 s23, s23, 0
	s_add_u32 s6, s6, 0x100
	s_addc_u32 s7, s7, 0
	s_cmp_ge_i32 s24, s14
	s_mov_b32 s8, s24
	s_cbranch_scc1 .LBB0_130

; #define PG8_STAGE(bufoff, gbase, voff) do { _Pragma("unroll") for (int _i = 0; _i < 2; ++_i) \
;         __builtin_amdgcn_global_load_lds((const unsigned*)((const char*)(gbase) + (voff)[_i]), (PG8_LAS unsigned*)(lds + (bufoff) + ldsw + _i * 8192), 16, 0, 0); } while (0)
; #define PG8_LDA(dst, b, h) do { _Pragma("unroll") for (int m = 0; m < 4; ++m) _Pragma("unroll") for (int k = 0; k < 2; ++k) dst[m][k] = *(const PG8_LAS bf16x8*)(lds + PG8_SA(b, h) + aoff + m * 2048 + k * 1024); } while (0)
; #define PG8_LDB(dst, b, h) do { _Pragma("unroll") for (int n = 0; n < 2; ++n) _Pragma("unroll") for (int k = 0; k < 2; ++k) dst[n][k] = *(const PG8_LAS bf16x8*)(lds + PG8_SB(b, h) + boff + n * 2048 + k * 1024); } while (0)
; #define PG8_MMA(ai, bj, At, Bt) do { __builtin_amdgcn_s_setprio(1); _Pragma("unroll") for (int m = 0; m < 4; ++m) _Pragma("unroll") for (int n = 0; n < 2; ++n) _Pragma("unroll") for (int k = 0; k < 2; ++k) \
;         acc[ai][bj][m][n] = __builtin_amdgcn_mfma_f32_16x16x32_bf16(Bt[n][k], At[m][k], acc[ai][bj][m][n], 0, 0, 0); __builtin_amdgcn_s_setprio(0); } while (0)
; #define PG8_WAIT_V(n) asm volatile("s_waitcnt vmcnt(" #n ")" ::: "memory")
;     ...
;         const bool has_next = S.next(ui + 1, nxt);
;         const char* nA = has_next ? (const char*)gA + (size_t)nxt.pm * tstepA + (size_t)nxt.pn * acolB : cA; const char* nB = has_next ? (const char*)gB + (size_t)nxt.pn * tstepB : cB;
;         for (int t = 0; t < nt; t += 2) {
;             const bool last = (t == nt - 2);
;             const char* a1 = cA + (size_t)(t + 1) * kstep;
;             const char* a2 = last ? nA : cA + (size_t)(t + 2) * kstep; const char* b2 = last ? nB : cB + (size_t)(t + 2) * kstep;
;             const char* a3 = a2 + kstep; const char* b3 = b2 + kstep;
;             if (last && has_next) S.a_ready(nxt);
;             if constexpr (SP2) {
;             PG8_LDB(B0, 0, 0); PG8_LDB(B1, 0, 1); PG8_SCHED; PG8_LDA(At, 0, 0); PG8_STAGE(PG8_SA(1, 1), a1 + hstepA, voffA);
;             PG8_WAIT_V(8); PG8_WAIT_L(0); PG8_BAR; PG8_MMA(0, 0, At, B0); PG8_MMA(0, 1, At, B1); PG8_BAR; PG8_SCHED;
;             PG8_LDA(At, 0, 1); PG8_STAGE(PG8_SB(0, 0), b2, voffB); PG8_STAGE(PG8_SB(0, 1), b2 + hstepB, voffB); PG8_STAGE(PG8_SA(0, 0), a2, voffA);
;             PG8_WAIT_V(8); PG8_WAIT_L(0); PG8_BAR; PG8_MMA(1, 0, At, B0); PG8_MMA(1, 1, At, B1); PG8_BAR; PG8_SCHED;
.LBB0_286:
	v_readlane_b32 s10, v255, 5
	v_readlane_b32 s11, v255, 6
	s_andn2_b64 vcc, exec, s[10:11]
	s_cbranch_vccnz .LBB0_289
	s_add_u32 s10, s6, 0x100
	s_addc_u32 s11, s7, 0
	s_add_u32 s6, s8, 0x80
	s_addc_u32 s7, s9, 0
	s_mov_b32 s8, 0
	s_add_i32 s12, s8, 2
	s_add_u32 s13, s6, 0x80
	s_addc_u32 s9, s7, 0
	s_add_i32 s16, 0, 0x10000
	s_cmp_eq_u32 s69, s8
	s_cselect_b32 s9, s41, s9
	s_cselect_b32 s8, s40, s13
	s_cselect_b32 s15, s5, s11
	s_cselect_b32 s14, s4, s10
	s_add_i32 s13, 0, 0x14000
	v_add_u32_e32 v142, s16, v249
	v_add_u32_e32 v158, s13, v249
	ds_read_b128 v[130:133], v142
	ds_read_b128 v[134:137], v142 offset:1024
	ds_read_b128 v[138:141], v142 offset:2048
	ds_read_b128 v[142:145], v142 offset:3072
	ds_read_b128 v[146:149], v158
	ds_read_b128 v[150:153], v158 offset:1024
	ds_read_b128 v[154:157], v158 offset:2048
	ds_read_b128 v[158:161], v158 offset:3072
	v_lshl_add_u64 v[212:213], s[6:7], 0, v[182:183]
	s_add_i32 m0, s27, 0xc000
	ds_read_b128 v[162:165], v251
	ds_read_b128 v[184:187], v251 offset:1024
	ds_read_b128 v[188:191], v251 offset:2048
	ds_read_b128 v[192:195], v251 offset:3072
	ds_read_b128 v[196:199], v251 offset:4096
	ds_read_b128 v[200:203], v251 offset:5120
	ds_read_b128 v[204:207], v251 offset:6144
	ds_read_b128 v[208:211], v251 offset:7168
	global_load_lds_dwordx4 v[212:213], off
	v_lshl_add_u64 v[212:213], s[6:7], 0, v[180:181]
	s_add_i32 m0, s27, 0xe000
	s_nop 0
	global_load_lds_dwordx4 v[212:213], off
	s_waitcnt vmcnt(8)
	s_waitcnt lgkmcnt(0)
	s_barrier
	s_setprio 1
	s_waitcnt lgkmcnt(0)
	v_mfma_f32_16x16x32_bf16 v[122:125], v[130:133], v[162:165], 0
	v_mfma_f32_16x16x32_bf16 v[118:121], v[138:141], v[162:165], 0
	v_mfma_f32_16x16x32_bf16 v[110:113], v[130:133], v[188:191], 0
	v_mfma_f32_16x16x32_bf16 v[102:105], v[138:141], v[188:191], 0
	v_mfma_f32_16x16x32_bf16 v[94:97], v[130:133], v[196:199], 0
	v_mfma_f32_16x16x32_bf16 v[86:89], v[138:141], v[196:199], 0
	v_mfma_f32_16x16x32_bf16 v[78:81], v[130:133], v[204:207], 0
	v_mfma_f32_16x16x32_bf16 v[70:73], v[138:141], v[204:207], 0
	v_mfma_f32_16x16x32_bf16 v[122:125], v[134:137], v[184:187], v[122:125]
	v_mfma_f32_16x16x32_bf16 v[118:121], v[142:145], v[184:187], v[118:121]
	v_mfma_f32_16x16x32_bf16 v[110:113], v[134:137], v[192:195], v[110:113]
	v_mfma_f32_16x16x32_bf16 v[102:105], v[142:145], v[192:195], v[102:105]
	v_mfma_f32_16x16x32_bf16 v[94:97], v[134:137], v[200:203], v[94:97]
	v_mfma_f32_16x16x32_bf16 v[86:89], v[142:145], v[200:203], v[86:89]
	v_mfma_f32_16x16x32_bf16 v[78:81], v[134:137], v[208:211], v[78:81]
	v_mfma_f32_16x16x32_bf16 v[70:73], v[142:145], v[208:211], v[70:73]
	s_setprio 0
	s_setprio 1
	v_mfma_f32_16x16x32_bf16 v[126:129], v[146:149], v[162:165], 0
	v_mfma_f32_16x16x32_bf16 v[114:117], v[154:157], v[162:165], 0
	v_mfma_f32_16x16x32_bf16 v[106:109], v[146:149], v[188:191], 0
	v_mfma_f32_16x16x32_bf16 v[98:101], v[154:157], v[188:191], 0
	v_mfma_f32_16x16x32_bf16 v[90:93], v[146:149], v[196:199], 0
	v_mfma_f32_16x16x32_bf16 v[82:85], v[154:157], v[196:199], 0
	v_mfma_f32_16x16x32_bf16 v[74:77], v[146:149], v[204:207], 0
	v_mfma_f32_16x16x32_bf16 v[66:69], v[154:157], v[204:207], 0
	v_mfma_f32_16x16x32_bf16 v[126:129], v[150:153], v[184:187], v[126:129]
	v_mfma_f32_16x16x32_bf16 v[114:117], v[158:161], v[184:187], v[114:117]
	v_mfma_f32_16x16x32_bf16 v[106:109], v[150:153], v[192:195], v[106:109]
	v_mfma_f32_16x16x32_bf16 v[98:101], v[158:161], v[192:195], v[98:101]
	v_mfma_f32_16x16x32_bf16 v[90:93], v[150:153], v[200:203], v[90:93]
	v_mfma_f32_16x16x32_bf16 v[82:85], v[158:161], v[200:203], v[82:85]
	v_mfma_f32_16x16x32_bf16 v[74:77], v[150:153], v[208:211], v[74:77]
	v_mfma_f32_16x16x32_bf16 v[66:69], v[158:161], v[208:211], v[66:69]
	s_setprio 0
	s_barrier
	s_add_i32 s16, s16, s0
	v_lshl_add_u64 v[212:213], s[14:15], 0, v[166:167]
	s_mov_b32 m0, s16
	ds_read_b128 v[162:165], v251 offset:16384
	ds_read_b128 v[184:187], v251 offset:17408
	ds_read_b128 v[188:191], v251 offset:18432
	ds_read_b128 v[192:195], v251 offset:19456
	ds_read_b128 v[196:199], v251 offset:20480
	ds_read_b128 v[200:203], v251 offset:21504
	ds_read_b128 v[204:207], v251 offset:22528
	ds_read_b128 v[208:211], v251 offset:23552
	global_load_lds_dwordx4 v[212:213], off
	s_add_i32 m0, s16, 0x2000
	v_lshl_add_u64 v[214:215], s[14:15], 0, v[172:173]
	s_add_u32 s14, s14, s58
	s_addc_u32 s15, s15, s59
	s_add_i32 s13, s13, s0
	global_load_lds_dwordx4 v[214:215], off
	v_lshl_add_u64 v[216:217], s[14:15], 0, v[166:167]
	s_mov_b32 m0, s13
	v_lshl_add_u64 v[218:219], s[14:15], 0, v[172:173]
	global_load_lds_dwordx4 v[216:217], off
	s_add_i32 m0, s13, 0x2000
	v_lshl_add_u64 v[220:221], s[8:9], 0, v[176:177]
	global_load_lds_dwordx4 v[218:219], off
	s_mov_b32 m0, s27
	v_lshl_add_u64 v[222:223], s[8:9], 0, v[174:175]
	global_load_lds_dwordx4 v[220:221], off
	s_mov_b32 m0, s31
	s_nop 0
	global_load_lds_dwordx4 v[222:223], off
	s_waitcnt vmcnt(8)
	s_waitcnt lgkmcnt(0)
	s_barrier
; #define PG8_STAGE(bufoff, gbase, voff) do { _Pragma("unroll") for (int _i = 0; _i < 2; ++_i) \
;         __builtin_amdgcn_global_load_lds((const unsigned*)((const char*)(gbase) + (voff)[_i]), (PG8_LAS unsigned*)(lds + (bufoff) + ldsw + _i * 8192), 16, 0, 0); } while (0)
; #define PG8_LDA(dst, b, h) do { _Pragma("unroll") for (int m = 0; m < 4; ++m) _Pragma("unroll") for (int k = 0; k < 2; ++k) dst[m][k] = *(const PG8_LAS bf16x8*)(lds + PG8_SA(b, h) + aoff + m * 2048 + k * 1024); } while (0)
; #define PG8_LDB(dst, b, h) do { _Pragma("unroll") for (int n = 0; n < 2; ++n) _Pragma("unroll") for (int k = 0; k < 2; ++k) dst[n][k] = *(const PG8_LAS bf16x8*)(lds + PG8_SB(b, h) + boff + n * 2048 + k * 1024); } while (0)
; #define PG8_MMA(ai, bj, At, Bt) do { __builtin_amdgcn_s_setprio(1); _Pragma("unroll") for (int m = 0; m < 4; ++m) _Pragma("unroll") for (int n = 0; n < 2; ++n) _Pragma("unroll") for (int k = 0; k < 2; ++k) \
;         acc[ai][bj][m][n] = __builtin_amdgcn_mfma_f32_16x16x32_bf16(Bt[n][k], At[m][k], acc[ai][bj][m][n], 0, 0, 0); __builtin_amdgcn_s_setprio(0); } while (0)
; #define PG8_WAIT_V(n) asm volatile("s_waitcnt vmcnt(" #n ")" ::: "memory")
; #define PG8_WAIT_L(n) asm volatile("s_waitcnt lgkmcnt(" #n ")" ::: "memory")
; #define PG8_BAR __builtin_amdgcn_s_barrier()
; #define PG8_SCHED __builtin_amdgcn_sched_barrier(0)
;     ...
;             PG8_WAIT_V(8); PG8_WAIT_L(0); PG8_BAR; PG8_MMA(1, 0, At, B0); PG8_MMA(1, 1, At, B1); PG8_BAR; PG8_SCHED;
;             PG8_LDB(B0, 1, 0); PG8_LDB(B1, 1, 1); PG8_SCHED; PG8_LDA(At, 1, 0); PG8_STAGE(PG8_SA(0, 1), a2 + hstepA, voffA);
;             PG8_WAIT_V(8); PG8_WAIT_L(0); PG8_BAR; PG8_MMA(0, 0, At, B0); PG8_MMA(0, 1, At, B1); PG8_BAR; PG8_SCHED;
	s_setprio 1
	s_waitcnt lgkmcnt(0)
	v_mfma_f32_16x16x32_bf16 v[62:65], v[130:133], v[162:165], 0
	v_mfma_f32_16x16x32_bf16 v[54:57], v[138:141], v[162:165], 0
	v_mfma_f32_16x16x32_bf16 v[46:49], v[130:133], v[188:191], 0
	v_mfma_f32_16x16x32_bf16 v[38:41], v[138:141], v[188:191], 0
	v_mfma_f32_16x16x32_bf16 v[30:33], v[130:133], v[196:199], 0
	v_mfma_f32_16x16x32_bf16 v[22:25], v[138:141], v[196:199], 0
	v_mfma_f32_16x16x32_bf16 v[14:17], v[130:133], v[204:207], 0
	v_mfma_f32_16x16x32_bf16 v[6:9], v[138:141], v[204:207], 0
	v_mfma_f32_16x16x32_bf16 v[62:65], v[134:137], v[184:187], v[62:65]
	v_mfma_f32_16x16x32_bf16 v[54:57], v[142:145], v[184:187], v[54:57]
	v_mfma_f32_16x16x32_bf16 v[46:49], v[134:137], v[192:195], v[46:49]
	v_mfma_f32_16x16x32_bf16 v[38:41], v[142:145], v[192:195], v[38:41]
	v_mfma_f32_16x16x32_bf16 v[30:33], v[134:137], v[200:203], v[30:33]
	v_mfma_f32_16x16x32_bf16 v[22:25], v[142:145], v[200:203], v[22:25]
	v_mfma_f32_16x16x32_bf16 v[14:17], v[134:137], v[208:211], v[14:17]
	v_mfma_f32_16x16x32_bf16 v[6:9], v[142:145], v[208:211], v[6:9]
	s_setprio 0
	s_setprio 1
	v_mfma_f32_16x16x32_bf16 v[58:61], v[146:149], v[162:165], 0
	v_mfma_f32_16x16x32_bf16 v[50:53], v[154:157], v[162:165], 0
	v_mfma_f32_16x16x32_bf16 v[42:45], v[146:149], v[188:191], 0
	v_mfma_f32_16x16x32_bf16 v[34:37], v[154:157], v[188:191], 0
	v_mfma_f32_16x16x32_bf16 v[26:29], v[146:149], v[196:199], 0
	v_mfma_f32_16x16x32_bf16 v[18:21], v[154:157], v[196:199], 0
	v_mfma_f32_16x16x32_bf16 v[10:13], v[146:149], v[204:207], 0
	v_mfma_f32_16x16x32_bf16 v[2:5], v[154:157], v[204:207], 0
	v_mfma_f32_16x16x32_bf16 v[58:61], v[150:153], v[184:187], v[58:61]
	v_mfma_f32_16x16x32_bf16 v[50:53], v[158:161], v[184:187], v[50:53]
	v_mfma_f32_16x16x32_bf16 v[42:45], v[150:153], v[192:195], v[42:45]
	v_mfma_f32_16x16x32_bf16 v[34:37], v[158:161], v[192:195], v[34:37]
	v_mfma_f32_16x16x32_bf16 v[26:29], v[150:153], v[200:203], v[26:29]
	v_mfma_f32_16x16x32_bf16 v[18:21], v[158:161], v[200:203], v[18:21]
	v_mfma_f32_16x16x32_bf16 v[10:13], v[150:153], v[208:211], v[10:13]
	v_mfma_f32_16x16x32_bf16 v[2:5], v[158:161], v[208:211], v[2:5]
	s_setprio 0
	s_barrier
	s_add_i32 s13, 0, 0x18000
	s_add_i32 s14, 0, 0x1c000
	v_add_u32_e32 v142, s13, v249
	v_add_u32_e32 v158, s14, v249
	ds_read_b128 v[130:133], v142
	ds_read_b128 v[134:137], v142 offset:1024
	ds_read_b128 v[138:141], v142 offset:2048
	ds_read_b128 v[142:145], v142 offset:3072
	ds_read_b128 v[146:149], v158
	ds_read_b128 v[150:153], v158 offset:1024
	ds_read_b128 v[154:157], v158 offset:2048
	ds_read_b128 v[158:161], v158 offset:3072
	s_add_u32 s8, s8, s58
	s_addc_u32 s9, s9, s59
	s_mov_b32 m0, s47
	v_lshl_add_u64 v[224:225], s[8:9], 0, v[176:177]
	ds_read_b128 v[162:165], v251 offset:32768
	ds_read_b128 v[184:187], v251 offset:33792
	ds_read_b128 v[188:191], v251 offset:34816
	ds_read_b128 v[192:195], v251 offset:35840
	ds_read_b128 v[196:199], v251 offset:36864
	ds_read_b128 v[200:203], v251 offset:37888
	ds_read_b128 v[204:207], v251 offset:38912
	ds_read_b128 v[208:211], v251 offset:39936
	global_load_lds_dwordx4 v[224:225], off
	v_lshl_add_u64 v[224:225], s[8:9], 0, v[174:175]
	s_mov_b32 m0, s49
	s_nop 0
	global_load_lds_dwordx4 v[224:225], off
	s_waitcnt vmcnt(8)
	s_waitcnt lgkmcnt(0)
	s_barrier
	s_setprio 1
	s_waitcnt lgkmcnt(0)
	v_mfma_f32_16x16x32_bf16 v[122:125], v[130:133], v[162:165], v[122:125]
	v_mfma_f32_16x16x32_bf16 v[118:121], v[138:141], v[162:165], v[118:121]
	v_mfma_f32_16x16x32_bf16 v[110:113], v[130:133], v[188:191], v[110:113]
	v_mfma_f32_16x16x32_bf16 v[102:105], v[138:141], v[188:191], v[102:105]
	v_mfma_f32_16x16x32_bf16 v[94:97], v[130:133], v[196:199], v[94:97]
	v_mfma_f32_16x16x32_bf16 v[86:89], v[138:141], v[196:199], v[86:89]
	v_mfma_f32_16x16x32_bf16 v[78:81], v[130:133], v[204:207], v[78:81]
	v_mfma_f32_16x16x32_bf16 v[70:73], v[138:141], v[204:207], v[70:73]
	v_mfma_f32_16x16x32_bf16 v[122:125], v[134:137], v[184:187], v[122:125]
	v_mfma_f32_16x16x32_bf16 v[118:121], v[142:145], v[184:187], v[118:121]
	v_mfma_f32_16x16x32_bf16 v[110:113], v[134:137], v[192:195], v[110:113]
	v_mfma_f32_16x16x32_bf16 v[102:105], v[142:145], v[192:195], v[102:105]
	v_mfma_f32_16x16x32_bf16 v[94:97], v[134:137], v[200:203], v[94:97]
	v_mfma_f32_16x16x32_bf16 v[86:89], v[142:145], v[200:203], v[86:89]
	v_mfma_f32_16x16x32_bf16 v[78:81], v[134:137], v[208:211], v[78:81]
	v_mfma_f32_16x16x32_bf16 v[70:73], v[142:145], v[208:211], v[70:73]
	s_setprio 0
	s_setprio 1
	v_mfma_f32_16x16x32_bf16 v[126:129], v[146:149], v[162:165], v[126:129]
	v_mfma_f32_16x16x32_bf16 v[114:117], v[154:157], v[162:165], v[114:117]
	v_mfma_f32_16x16x32_bf16 v[106:109], v[146:149], v[188:191], v[106:109]
	v_mfma_f32_16x16x32_bf16 v[98:101], v[154:157], v[188:191], v[98:101]
	v_mfma_f32_16x16x32_bf16 v[90:93], v[146:149], v[196:199], v[90:93]
	v_mfma_f32_16x16x32_bf16 v[82:85], v[154:157], v[196:199], v[82:85]
	v_mfma_f32_16x16x32_bf16 v[74:77], v[146:149], v[204:207], v[74:77]
	v_mfma_f32_16x16x32_bf16 v[66:69], v[154:157], v[204:207], v[66:69]
	v_mfma_f32_16x16x32_bf16 v[126:129], v[150:153], v[184:187], v[126:129]
	v_mfma_f32_16x16x32_bf16 v[114:117], v[158:161], v[184:187], v[114:117]
	v_mfma_f32_16x16x32_bf16 v[106:109], v[150:153], v[192:195], v[106:109]
	v_mfma_f32_16x16x32_bf16 v[98:101], v[158:161], v[192:195], v[98:101]
	v_mfma_f32_16x16x32_bf16 v[90:93], v[150:153], v[200:203], v[90:93]
	v_mfma_f32_16x16x32_bf16 v[82:85], v[158:161], v[200:203], v[82:85]
	v_mfma_f32_16x16x32_bf16 v[74:77], v[150:153], v[208:211], v[74:77]
	v_mfma_f32_16x16x32_bf16 v[66:69], v[158:161], v[208:211], v[66:69]
	s_setprio 0
	s_barrier
; #define PG8_STAGE(bufoff, gbase, voff) do { _Pragma("unroll") for (int _i = 0; _i < 2; ++_i) \
;         __builtin_amdgcn_global_load_lds((const unsigned*)((const char*)(gbase) + (voff)[_i]), (PG8_LAS unsigned*)(lds + (bufoff) + ldsw + _i * 8192), 16, 0, 0); } while (0)
; #define PG8_LDA(dst, b, h) do { _Pragma("unroll") for (int m = 0; m < 4; ++m) _Pragma("unroll") for (int k = 0; k < 2; ++k) dst[m][k] = *(const PG8_LAS bf16x8*)(lds + PG8_SA(b, h) + aoff + m * 2048 + k * 1024); } while (0)
; #define PG8_MMA(ai, bj, At, Bt) do { __builtin_amdgcn_s_setprio(1); _Pragma("unroll") for (int m = 0; m < 4; ++m) _Pragma("unroll") for (int n = 0; n < 2; ++n) _Pragma("unroll") for (int k = 0; k < 2; ++k) \
;         acc[ai][bj][m][n] = __builtin_amdgcn_mfma_f32_16x16x32_bf16(Bt[n][k], At[m][k], acc[ai][bj][m][n], 0, 0, 0); __builtin_amdgcn_s_setprio(0); } while (0)
; #define PG8_WAIT_V(n) asm volatile("s_waitcnt vmcnt(" #n ")" ::: "memory")
; #define PG8_WAIT_L(n) asm volatile("s_waitcnt lgkmcnt(" #n ")" ::: "memory")
; #define PG8_BAR __builtin_amdgcn_s_barrier()
; #define PG8_SCHED __builtin_amdgcn_sched_barrier(0)
;     ...
;             PG8_LDA(At, 1, 1); PG8_STAGE(PG8_SB(1, 0), b3, voffB); PG8_STAGE(PG8_SB(1, 1), b3 + hstepB, voffB); PG8_STAGE(PG8_SA(1, 0), a3, voffA);
;             PG8_WAIT_V(8); PG8_WAIT_L(0); PG8_BAR; PG8_MMA(1, 0, At, B0); PG8_MMA(1, 1, At, B1); PG8_BAR; PG8_SCHED;
	s_add_i32 s8, s13, s0
	v_lshl_add_u64 v[212:213], v[212:213], 0, s[62:63]
	s_mov_b32 m0, s8
	ds_read_b128 v[162:165], v251 offset:49152
	ds_read_b128 v[184:187], v251 offset:50176
	ds_read_b128 v[188:191], v251 offset:51200
	ds_read_b128 v[192:195], v251 offset:52224
	ds_read_b128 v[196:199], v251 offset:53248
	ds_read_b128 v[200:203], v251 offset:54272
	ds_read_b128 v[204:207], v251 offset:55296
	ds_read_b128 v[208:211], v251 offset:56320
	global_load_lds_dwordx4 v[212:213], off
	v_lshl_add_u64 v[212:213], v[214:215], 0, s[62:63]
	s_add_i32 m0, s8, 0x2000
	s_add_i32 s8, s14, s0
	global_load_lds_dwordx4 v[212:213], off
	v_lshl_add_u64 v[212:213], v[216:217], 0, s[62:63]
	s_mov_b32 m0, s8
	s_nop 0
	global_load_lds_dwordx4 v[212:213], off
	v_lshl_add_u64 v[212:213], v[218:219], 0, s[62:63]
	s_add_i32 m0, s8, 0x2000
	s_nop 0
	global_load_lds_dwordx4 v[212:213], off
	v_lshl_add_u64 v[212:213], v[220:221], 0, s[62:63]
	s_mov_b32 m0, s51
	s_nop 0
	global_load_lds_dwordx4 v[212:213], off
	v_lshl_add_u64 v[212:213], v[222:223], 0, s[62:63]
	s_mov_b32 m0, s53
	s_nop 0
	global_load_lds_dwordx4 v[212:213], off
	s_waitcnt vmcnt(8)
	s_waitcnt lgkmcnt(0)
	s_barrier
	s_setprio 1
	s_waitcnt lgkmcnt(0)
	v_mfma_f32_16x16x32_bf16 v[62:65], v[130:133], v[162:165], v[62:65]
	v_mfma_f32_16x16x32_bf16 v[54:57], v[138:141], v[162:165], v[54:57]
	v_mfma_f32_16x16x32_bf16 v[46:49], v[130:133], v[188:191], v[46:49]
	v_mfma_f32_16x16x32_bf16 v[38:41], v[138:141], v[188:191], v[38:41]
	v_mfma_f32_16x16x32_bf16 v[30:33], v[130:133], v[196:199], v[30:33]
	v_mfma_f32_16x16x32_bf16 v[22:25], v[138:141], v[196:199], v[22:25]
	v_mfma_f32_16x16x32_bf16 v[14:17], v[130:133], v[204:207], v[14:17]
	v_mfma_f32_16x16x32_bf16 v[6:9], v[138:141], v[204:207], v[6:9]
	v_mfma_f32_16x16x32_bf16 v[62:65], v[134:137], v[184:187], v[62:65]
	v_mfma_f32_16x16x32_bf16 v[54:57], v[142:145], v[184:187], v[54:57]
	v_mfma_f32_16x16x32_bf16 v[46:49], v[134:137], v[192:195], v[46:49]
	v_mfma_f32_16x16x32_bf16 v[38:41], v[142:145], v[192:195], v[38:41]
	v_mfma_f32_16x16x32_bf16 v[30:33], v[134:137], v[200:203], v[30:33]
	v_mfma_f32_16x16x32_bf16 v[22:25], v[142:145], v[200:203], v[22:25]
	v_mfma_f32_16x16x32_bf16 v[14:17], v[134:137], v[208:211], v[14:17]
	v_mfma_f32_16x16x32_bf16 v[6:9], v[142:145], v[208:211], v[6:9]
	s_setprio 0
	s_setprio 1
	v_mfma_f32_16x16x32_bf16 v[58:61], v[146:149], v[162:165], v[58:61]
	v_mfma_f32_16x16x32_bf16 v[50:53], v[154:157], v[162:165], v[50:53]
	v_mfma_f32_16x16x32_bf16 v[42:45], v[146:149], v[188:191], v[42:45]
	v_mfma_f32_16x16x32_bf16 v[34:37], v[154:157], v[188:191], v[34:37]
	v_mfma_f32_16x16x32_bf16 v[26:29], v[146:149], v[196:199], v[26:29]
	v_mfma_f32_16x16x32_bf16 v[18:21], v[154:157], v[196:199], v[18:21]
	v_mfma_f32_16x16x32_bf16 v[10:13], v[146:149], v[204:207], v[10:13]
	v_mfma_f32_16x16x32_bf16 v[2:5], v[154:157], v[204:207], v[2:5]
	v_mfma_f32_16x16x32_bf16 v[58:61], v[150:153], v[184:187], v[58:61]
	v_mfma_f32_16x16x32_bf16 v[50:53], v[158:161], v[184:187], v[50:53]
	v_mfma_f32_16x16x32_bf16 v[42:45], v[150:153], v[192:195], v[42:45]
	v_mfma_f32_16x16x32_bf16 v[34:37], v[158:161], v[192:195], v[34:37]
	v_mfma_f32_16x16x32_bf16 v[26:29], v[150:153], v[200:203], v[26:29]
	v_mfma_f32_16x16x32_bf16 v[18:21], v[158:161], v[200:203], v[18:21]
	v_mfma_f32_16x16x32_bf16 v[10:13], v[150:153], v[208:211], v[10:13]
	v_mfma_f32_16x16x32_bf16 v[2:5], v[158:161], v[208:211], v[2:5]
	s_setprio 0
	s_barrier
	s_add_u32 s10, s10, 0x100
	s_addc_u32 s11, s11, 0
	s_add_u32 s6, s6, 0x100
	s_addc_u32 s7, s7, 0
	s_cmp_ge_i32 s12, s55
	s_mov_b32 s8, s12
	s_cbranch_scc1 .LBB0_289

; #define PG8_STAGE(bufoff, gbase, voff) do { _Pragma("unroll") for (int _i = 0; _i < 2; ++_i) \
;         __builtin_amdgcn_global_load_lds((const unsigned*)((const char*)(gbase) + (voff)[_i]), (PG8_LAS unsigned*)(lds + (bufoff) + ldsw + _i * 8192), 16, 0, 0); } while (0)
; #define PG8_LDA(dst, b, h) do { _Pragma("unroll") for (int m = 0; m < 4; ++m) _Pragma("unroll") for (int k = 0; k < 2; ++k) dst[m][k] = *(const PG8_LAS bf16x8*)(lds + PG8_SA(b, h) + aoff + m * 2048 + k * 1024); } while (0)
; #define PG8_LDB(dst, b, h) do { _Pragma("unroll") for (int n = 0; n < 2; ++n) _Pragma("unroll") for (int k = 0; k < 2; ++k) dst[n][k] = *(const PG8_LAS bf16x8*)(lds + PG8_SB(b, h) + boff + n * 2048 + k * 1024); } while (0)
; #define PG8_MMA(ai, bj, At, Bt) do { __builtin_amdgcn_s_setprio(1); _Pragma("unroll") for (int m = 0; m < 4; ++m) _Pragma("unroll") for (int n = 0; n < 2; ++n) _Pragma("unroll") for (int k = 0; k < 2; ++k) \
;         acc[ai][bj][m][n] = __builtin_amdgcn_mfma_f32_16x16x32_bf16(Bt[n][k], At[m][k], acc[ai][bj][m][n], 0, 0, 0); __builtin_amdgcn_s_setprio(0); } while (0)
; #define PG8_WAIT_V(n) asm volatile("s_waitcnt vmcnt(" #n ")" ::: "memory")
;     ...
;         const bool has_next = S.next(ui + 1, nxt);
;         const char* nA = has_next ? (const char*)gA + (size_t)nxt.pm * tstepA + (size_t)nxt.pn * acolB : cA; const char* nB = has_next ? (const char*)gB + (size_t)nxt.pn * tstepB : cB;
;         for (int t = 0; t < nt; t += 2) {
;             const bool last = (t == nt - 2);
;             const char* a1 = cA + (size_t)(t + 1) * kstep;
;             const char* a2 = last ? nA : cA + (size_t)(t + 2) * kstep; const char* b2 = last ? nB : cB + (size_t)(t + 2) * kstep;
;             const char* a3 = a2 + kstep; const char* b3 = b2 + kstep;
;             if (last && has_next) S.a_ready(nxt);
;             if constexpr (SP2) {
;             PG8_LDB(B0, 0, 0); PG8_LDB(B1, 0, 1); PG8_SCHED; PG8_LDA(At, 0, 0); PG8_STAGE(PG8_SA(1, 1), a1 + hstepA, voffA);
;             PG8_WAIT_V(8); PG8_WAIT_L(0); PG8_BAR; PG8_MMA(0, 0, At, B0); PG8_MMA(0, 1, At, B1); PG8_BAR; PG8_SCHED;
;             PG8_LDA(At, 0, 1); PG8_STAGE(PG8_SB(0, 0), b2, voffB); PG8_STAGE(PG8_SB(0, 1), b2 + hstepB, voffB); PG8_STAGE(PG8_SA(0, 0), a2, voffA);
;             PG8_WAIT_V(8); PG8_WAIT_L(0); PG8_BAR; PG8_MMA(1, 0, At, B0); PG8_MMA(1, 1, At, B1); PG8_BAR; PG8_SCHED;
.LBB0_518:
	s_andn2_b64 vcc, exec, s[88:89]
	s_waitcnt lgkmcnt(0)
	s_cbranch_vccnz .LBB0_521
	s_add_u32 s10, s6, 0x100
	s_addc_u32 s11, s7, 0
	s_add_u32 s6, s8, 0x80
	s_addc_u32 s7, s9, 0
	s_mov_b32 s8, 0
	s_add_i32 s25, s8, 2
	s_add_u32 s27, s6, 0x80
	s_addc_u32 s9, s7, 0
	s_add_i32 s31, 0, 0x10000
	s_cmp_eq_u32 s19, s8
	s_cselect_b32 s9, s43, s9
	s_cselect_b32 s8, s42, s27
	s_cselect_b32 s35, s93, s11
	s_cselect_b32 s34, s92, s10
	s_add_i32 s27, 0, 0x14000
	v_add_u32_e32 v148, s31, v229
	v_add_u32_e32 v164, s27, v229
	ds_read_b128 v[136:139], v148
	ds_read_b128 v[140:143], v148 offset:1024
	ds_read_b128 v[144:147], v148 offset:2048
	ds_read_b128 v[148:151], v148 offset:3072
	ds_read_b128 v[152:155], v164
	ds_read_b128 v[156:159], v164 offset:1024
	ds_read_b128 v[160:163], v164 offset:2048
	ds_read_b128 v[172:175], v164 offset:3072
	v_lshl_add_u64 v[164:165], s[6:7], 0, v[134:135]
	s_add_i32 m0, s2, 0xc000
	ds_read_b128 v[176:179], v231
	ds_read_b128 v[180:183], v231 offset:1024
	ds_read_b128 v[184:187], v231 offset:2048
	ds_read_b128 v[188:191], v231 offset:3072
	ds_read_b128 v[192:195], v231 offset:4096
	ds_read_b128 v[196:199], v231 offset:5120
	ds_read_b128 v[200:203], v231 offset:6144
	ds_read_b128 v[204:207], v231 offset:7168
	global_load_lds_dwordx4 v[164:165], off
	v_lshl_add_u64 v[164:165], s[6:7], 0, v[132:133]
	s_add_i32 m0, s2, 0xe000
	s_nop 0
	global_load_lds_dwordx4 v[164:165], off
	s_waitcnt vmcnt(8)
	s_waitcnt lgkmcnt(0)
	s_barrier
	s_setprio 1
	s_waitcnt lgkmcnt(0)
	v_mfma_f32_16x16x32_bf16 v[126:129], v[136:139], v[176:179], 0
	v_mfma_f32_16x16x32_bf16 v[122:125], v[144:147], v[176:179], 0
	v_mfma_f32_16x16x32_bf16 v[110:113], v[136:139], v[184:187], 0
	v_mfma_f32_16x16x32_bf16 v[106:109], v[144:147], v[184:187], 0
	v_mfma_f32_16x16x32_bf16 v[94:97], v[136:139], v[192:195], 0
	v_mfma_f32_16x16x32_bf16 v[90:93], v[144:147], v[192:195], 0
	v_mfma_f32_16x16x32_bf16 v[78:81], v[136:139], v[200:203], 0
	v_mfma_f32_16x16x32_bf16 v[74:77], v[144:147], v[200:203], 0
	v_mfma_f32_16x16x32_bf16 v[126:129], v[140:143], v[180:183], v[126:129]
	v_mfma_f32_16x16x32_bf16 v[122:125], v[148:151], v[180:183], v[122:125]
	v_mfma_f32_16x16x32_bf16 v[110:113], v[140:143], v[188:191], v[110:113]
	v_mfma_f32_16x16x32_bf16 v[106:109], v[148:151], v[188:191], v[106:109]
	v_mfma_f32_16x16x32_bf16 v[94:97], v[140:143], v[196:199], v[94:97]
	v_mfma_f32_16x16x32_bf16 v[90:93], v[148:151], v[196:199], v[90:93]
	v_mfma_f32_16x16x32_bf16 v[78:81], v[140:143], v[204:207], v[78:81]
	v_mfma_f32_16x16x32_bf16 v[74:77], v[148:151], v[204:207], v[74:77]
	s_setprio 0
	s_setprio 1
	v_mfma_f32_16x16x32_bf16 v[118:121], v[152:155], v[176:179], 0
	v_mfma_f32_16x16x32_bf16 v[114:117], v[160:163], v[176:179], 0
	v_mfma_f32_16x16x32_bf16 v[102:105], v[152:155], v[184:187], 0
	v_mfma_f32_16x16x32_bf16 v[98:101], v[160:163], v[184:187], 0
	v_mfma_f32_16x16x32_bf16 v[86:89], v[152:155], v[192:195], 0
	v_mfma_f32_16x16x32_bf16 v[82:85], v[160:163], v[192:195], 0
	v_mfma_f32_16x16x32_bf16 v[70:73], v[152:155], v[200:203], 0
	v_mfma_f32_16x16x32_bf16 v[66:69], v[160:163], v[200:203], 0
	v_mfma_f32_16x16x32_bf16 v[118:121], v[156:159], v[180:183], v[118:121]
	v_mfma_f32_16x16x32_bf16 v[114:117], v[172:175], v[180:183], v[114:117]
	v_mfma_f32_16x16x32_bf16 v[102:105], v[156:159], v[188:191], v[102:105]
	v_mfma_f32_16x16x32_bf16 v[98:101], v[172:175], v[188:191], v[98:101]
	v_mfma_f32_16x16x32_bf16 v[86:89], v[156:159], v[196:199], v[86:89]
	v_mfma_f32_16x16x32_bf16 v[82:85], v[172:175], v[196:199], v[82:85]
	v_mfma_f32_16x16x32_bf16 v[70:73], v[156:159], v[204:207], v[70:73]
	v_mfma_f32_16x16x32_bf16 v[66:69], v[172:175], v[204:207], v[66:69]
	s_setprio 0
	s_barrier
	s_add_i32 s31, s31, s0
	v_lshl_add_u64 v[164:165], s[34:35], 0, v[166:167]
	s_mov_b32 m0, s31
	ds_read_b128 v[176:179], v231 offset:16384
	ds_read_b128 v[180:183], v231 offset:17408
	ds_read_b128 v[184:187], v231 offset:18432
	ds_read_b128 v[188:191], v231 offset:19456
	ds_read_b128 v[192:195], v231 offset:20480
	ds_read_b128 v[196:199], v231 offset:21504
	ds_read_b128 v[200:203], v231 offset:22528
	ds_read_b128 v[204:207], v231 offset:23552
	global_load_lds_dwordx4 v[164:165], off
	s_add_i32 m0, s31, 0x2000
	v_lshl_add_u64 v[168:169], s[34:35], 0, v[130:131]
	s_add_u32 s34, s34, s60
	s_addc_u32 s35, s35, s61
	s_add_i32 s27, s27, s0
	global_load_lds_dwordx4 v[168:169], off
	v_lshl_add_u64 v[170:171], s[34:35], 0, v[166:167]
	s_mov_b32 m0, s27
	v_lshl_add_u64 v[208:209], s[34:35], 0, v[130:131]
	global_load_lds_dwordx4 v[170:171], off
	s_add_i32 m0, s27, 0x2000
	v_lshl_add_u64 v[210:211], s[8:9], 0, v[166:167]
	global_load_lds_dwordx4 v[208:209], off
	s_mov_b32 m0, s2
	v_lshl_add_u64 v[212:213], s[8:9], 0, v[130:131]
	global_load_lds_dwordx4 v[210:211], off
	s_mov_b32 m0, s3
	s_nop 0
	global_load_lds_dwordx4 v[212:213], off
	s_waitcnt vmcnt(8)
	s_waitcnt lgkmcnt(0)
	s_barrier
; #define PG8_STAGE(bufoff, gbase, voff) do { _Pragma("unroll") for (int _i = 0; _i < 2; ++_i) \
;         __builtin_amdgcn_global_load_lds((const unsigned*)((const char*)(gbase) + (voff)[_i]), (PG8_LAS unsigned*)(lds + (bufoff) + ldsw + _i * 8192), 16, 0, 0); } while (0)
; #define PG8_LDA(dst, b, h) do { _Pragma("unroll") for (int m = 0; m < 4; ++m) _Pragma("unroll") for (int k = 0; k < 2; ++k) dst[m][k] = *(const PG8_LAS bf16x8*)(lds + PG8_SA(b, h) + aoff + m * 2048 + k * 1024); } while (0)
; #define PG8_LDB(dst, b, h) do { _Pragma("unroll") for (int n = 0; n < 2; ++n) _Pragma("unroll") for (int k = 0; k < 2; ++k) dst[n][k] = *(const PG8_LAS bf16x8*)(lds + PG8_SB(b, h) + boff + n * 2048 + k * 1024); } while (0)
; #define PG8_MMA(ai, bj, At, Bt) do { __builtin_amdgcn_s_setprio(1); _Pragma("unroll") for (int m = 0; m < 4; ++m) _Pragma("unroll") for (int n = 0; n < 2; ++n) _Pragma("unroll") for (int k = 0; k < 2; ++k) \
;         acc[ai][bj][m][n] = __builtin_amdgcn_mfma_f32_16x16x32_bf16(Bt[n][k], At[m][k], acc[ai][bj][m][n], 0, 0, 0); __builtin_amdgcn_s_setprio(0); } while (0)
; #define PG8_WAIT_V(n) asm volatile("s_waitcnt vmcnt(" #n ")" ::: "memory")
; #define PG8_WAIT_L(n) asm volatile("s_waitcnt lgkmcnt(" #n ")" ::: "memory")
; #define PG8_BAR __builtin_amdgcn_s_barrier()
; #define PG8_SCHED __builtin_amdgcn_sched_barrier(0)
;     ...
;             PG8_WAIT_V(8); PG8_WAIT_L(0); PG8_BAR; PG8_MMA(1, 0, At, B0); PG8_MMA(1, 1, At, B1); PG8_BAR; PG8_SCHED;
;             PG8_LDB(B0, 1, 0); PG8_LDB(B1, 1, 1); PG8_SCHED; PG8_LDA(At, 1, 0); PG8_STAGE(PG8_SA(0, 1), a2 + hstepA, voffA);
;             PG8_WAIT_V(8); PG8_WAIT_L(0); PG8_BAR; PG8_MMA(0, 0, At, B0); PG8_MMA(0, 1, At, B1); PG8_BAR; PG8_SCHED;
	s_setprio 1
	s_waitcnt lgkmcnt(0)
	v_mfma_f32_16x16x32_bf16 v[62:65], v[136:139], v[176:179], 0
	v_mfma_f32_16x16x32_bf16 v[58:61], v[144:147], v[176:179], 0
	v_mfma_f32_16x16x32_bf16 v[46:49], v[136:139], v[184:187], 0
	v_mfma_f32_16x16x32_bf16 v[42:45], v[144:147], v[184:187], 0
	v_mfma_f32_16x16x32_bf16 v[30:33], v[136:139], v[192:195], 0
	v_mfma_f32_16x16x32_bf16 v[26:29], v[144:147], v[192:195], 0
	v_mfma_f32_16x16x32_bf16 v[14:17], v[136:139], v[200:203], 0
	v_mfma_f32_16x16x32_bf16 v[10:13], v[144:147], v[200:203], 0
	v_mfma_f32_16x16x32_bf16 v[62:65], v[140:143], v[180:183], v[62:65]
	v_mfma_f32_16x16x32_bf16 v[58:61], v[148:151], v[180:183], v[58:61]
	v_mfma_f32_16x16x32_bf16 v[46:49], v[140:143], v[188:191], v[46:49]
	v_mfma_f32_16x16x32_bf16 v[42:45], v[148:151], v[188:191], v[42:45]
	v_mfma_f32_16x16x32_bf16 v[30:33], v[140:143], v[196:199], v[30:33]
	v_mfma_f32_16x16x32_bf16 v[26:29], v[148:151], v[196:199], v[26:29]
	v_mfma_f32_16x16x32_bf16 v[14:17], v[140:143], v[204:207], v[14:17]
	v_mfma_f32_16x16x32_bf16 v[10:13], v[148:151], v[204:207], v[10:13]
	s_setprio 0
	s_setprio 1
	v_mfma_f32_16x16x32_bf16 v[54:57], v[152:155], v[176:179], 0
	v_mfma_f32_16x16x32_bf16 v[50:53], v[160:163], v[176:179], 0
	v_mfma_f32_16x16x32_bf16 v[38:41], v[152:155], v[184:187], 0
	v_mfma_f32_16x16x32_bf16 v[34:37], v[160:163], v[184:187], 0
	v_mfma_f32_16x16x32_bf16 v[22:25], v[152:155], v[192:195], 0
	v_mfma_f32_16x16x32_bf16 v[18:21], v[160:163], v[192:195], 0
	v_mfma_f32_16x16x32_bf16 v[6:9], v[152:155], v[200:203], 0
	v_mfma_f32_16x16x32_bf16 v[2:5], v[160:163], v[200:203], 0
	v_mfma_f32_16x16x32_bf16 v[54:57], v[156:159], v[180:183], v[54:57]
	v_mfma_f32_16x16x32_bf16 v[50:53], v[172:175], v[180:183], v[50:53]
	v_mfma_f32_16x16x32_bf16 v[38:41], v[156:159], v[188:191], v[38:41]
	v_mfma_f32_16x16x32_bf16 v[34:37], v[172:175], v[188:191], v[34:37]
	v_mfma_f32_16x16x32_bf16 v[22:25], v[156:159], v[196:199], v[22:25]
	v_mfma_f32_16x16x32_bf16 v[18:21], v[172:175], v[196:199], v[18:21]
	v_mfma_f32_16x16x32_bf16 v[6:9], v[156:159], v[204:207], v[6:9]
	v_mfma_f32_16x16x32_bf16 v[2:5], v[172:175], v[204:207], v[2:5]
	s_setprio 0
	s_barrier
	s_add_i32 s27, 0, 0x18000
	s_add_i32 s31, 0, 0x1c000
	v_add_u32_e32 v148, s27, v229
	v_add_u32_e32 v172, s31, v229
	ds_read_b128 v[136:139], v148
	ds_read_b128 v[140:143], v148 offset:1024
	ds_read_b128 v[144:147], v148 offset:2048
	ds_read_b128 v[148:151], v148 offset:3072
	ds_read_b128 v[152:155], v172
	ds_read_b128 v[156:159], v172 offset:1024
	ds_read_b128 v[160:163], v172 offset:2048
	ds_read_b128 v[172:175], v172 offset:3072
	s_add_u32 s8, s8, s60
	s_addc_u32 s9, s9, s61
	s_mov_b32 m0, s14
	v_lshl_add_u64 v[214:215], s[8:9], 0, v[166:167]
	ds_read_b128 v[176:179], v231 offset:32768
	ds_read_b128 v[180:183], v231 offset:33792
	ds_read_b128 v[184:187], v231 offset:34816
	ds_read_b128 v[188:191], v231 offset:35840
	ds_read_b128 v[192:195], v231 offset:36864
	ds_read_b128 v[196:199], v231 offset:37888
	ds_read_b128 v[200:203], v231 offset:38912
	ds_read_b128 v[204:207], v231 offset:39936
	global_load_lds_dwordx4 v[214:215], off
	v_lshl_add_u64 v[214:215], s[8:9], 0, v[130:131]
	s_mov_b32 m0, s15
	s_nop 0
	global_load_lds_dwordx4 v[214:215], off
	s_waitcnt vmcnt(8)
	s_waitcnt lgkmcnt(0)
	s_barrier
	s_setprio 1
	s_waitcnt lgkmcnt(0)
	v_mfma_f32_16x16x32_bf16 v[126:129], v[136:139], v[176:179], v[126:129]
	v_mfma_f32_16x16x32_bf16 v[122:125], v[144:147], v[176:179], v[122:125]
	v_mfma_f32_16x16x32_bf16 v[110:113], v[136:139], v[184:187], v[110:113]
	v_mfma_f32_16x16x32_bf16 v[106:109], v[144:147], v[184:187], v[106:109]
	v_mfma_f32_16x16x32_bf16 v[94:97], v[136:139], v[192:195], v[94:97]
	v_mfma_f32_16x16x32_bf16 v[90:93], v[144:147], v[192:195], v[90:93]
	v_mfma_f32_16x16x32_bf16 v[78:81], v[136:139], v[200:203], v[78:81]
	v_mfma_f32_16x16x32_bf16 v[74:77], v[144:147], v[200:203], v[74:77]
	v_mfma_f32_16x16x32_bf16 v[126:129], v[140:143], v[180:183], v[126:129]
	v_mfma_f32_16x16x32_bf16 v[122:125], v[148:151], v[180:183], v[122:125]
	v_mfma_f32_16x16x32_bf16 v[110:113], v[140:143], v[188:191], v[110:113]
	v_mfma_f32_16x16x32_bf16 v[106:109], v[148:151], v[188:191], v[106:109]
	v_mfma_f32_16x16x32_bf16 v[94:97], v[140:143], v[196:199], v[94:97]
	v_mfma_f32_16x16x32_bf16 v[90:93], v[148:151], v[196:199], v[90:93]
	v_mfma_f32_16x16x32_bf16 v[78:81], v[140:143], v[204:207], v[78:81]
	v_mfma_f32_16x16x32_bf16 v[74:77], v[148:151], v[204:207], v[74:77]
	s_setprio 0
	s_setprio 1
	v_mfma_f32_16x16x32_bf16 v[118:121], v[152:155], v[176:179], v[118:121]
	v_mfma_f32_16x16x32_bf16 v[114:117], v[160:163], v[176:179], v[114:117]
	v_mfma_f32_16x16x32_bf16 v[102:105], v[152:155], v[184:187], v[102:105]
	v_mfma_f32_16x16x32_bf16 v[98:101], v[160:163], v[184:187], v[98:101]
	v_mfma_f32_16x16x32_bf16 v[86:89], v[152:155], v[192:195], v[86:89]
	v_mfma_f32_16x16x32_bf16 v[82:85], v[160:163], v[192:195], v[82:85]
	v_mfma_f32_16x16x32_bf16 v[70:73], v[152:155], v[200:203], v[70:73]
	v_mfma_f32_16x16x32_bf16 v[66:69], v[160:163], v[200:203], v[66:69]
	v_mfma_f32_16x16x32_bf16 v[118:121], v[156:159], v[180:183], v[118:121]
	v_mfma_f32_16x16x32_bf16 v[114:117], v[172:175], v[180:183], v[114:117]
	v_mfma_f32_16x16x32_bf16 v[102:105], v[156:159], v[188:191], v[102:105]
	v_mfma_f32_16x16x32_bf16 v[98:101], v[172:175], v[188:191], v[98:101]
	v_mfma_f32_16x16x32_bf16 v[86:89], v[156:159], v[196:199], v[86:89]
	v_mfma_f32_16x16x32_bf16 v[82:85], v[172:175], v[196:199], v[82:85]
	v_mfma_f32_16x16x32_bf16 v[70:73], v[156:159], v[204:207], v[70:73]
	v_mfma_f32_16x16x32_bf16 v[66:69], v[172:175], v[204:207], v[66:69]
	s_setprio 0
	s_barrier
; #define PG8_STAGE(bufoff, gbase, voff) do { _Pragma("unroll") for (int _i = 0; _i < 2; ++_i) \
;         __builtin_amdgcn_global_load_lds((const unsigned*)((const char*)(gbase) + (voff)[_i]), (PG8_LAS unsigned*)(lds + (bufoff) + ldsw + _i * 8192), 16, 0, 0); } while (0)
; #define PG8_LDA(dst, b, h) do { _Pragma("unroll") for (int m = 0; m < 4; ++m) _Pragma("unroll") for (int k = 0; k < 2; ++k) dst[m][k] = *(const PG8_LAS bf16x8*)(lds + PG8_SA(b, h) + aoff + m * 2048 + k * 1024); } while (0)
; #define PG8_MMA(ai, bj, At, Bt) do { __builtin_amdgcn_s_setprio(1); _Pragma("unroll") for (int m = 0; m < 4; ++m) _Pragma("unroll") for (int n = 0; n < 2; ++n) _Pragma("unroll") for (int k = 0; k < 2; ++k) \
;         acc[ai][bj][m][n] = __builtin_amdgcn_mfma_f32_16x16x32_bf16(Bt[n][k], At[m][k], acc[ai][bj][m][n], 0, 0, 0); __builtin_amdgcn_s_setprio(0); } while (0)
; #define PG8_WAIT_V(n) asm volatile("s_waitcnt vmcnt(" #n ")" ::: "memory")
; #define PG8_WAIT_L(n) asm volatile("s_waitcnt lgkmcnt(" #n ")" ::: "memory")
; #define PG8_BAR __builtin_amdgcn_s_barrier()
; #define PG8_SCHED __builtin_amdgcn_sched_barrier(0)
;     ...
;             PG8_LDA(At, 1, 1); PG8_STAGE(PG8_SB(1, 0), b3, voffB); PG8_STAGE(PG8_SB(1, 1), b3 + hstepB, voffB); PG8_STAGE(PG8_SA(1, 0), a3, voffA);
;             PG8_WAIT_V(8); PG8_WAIT_L(0); PG8_BAR; PG8_MMA(1, 0, At, B0); PG8_MMA(1, 1, At, B1); PG8_BAR; PG8_SCHED;
	s_add_i32 s8, s27, s0
	v_lshl_add_u64 v[164:165], v[164:165], 0, s[62:63]
	s_mov_b32 m0, s8
	ds_read_b128 v[176:179], v231 offset:49152
	ds_read_b128 v[180:183], v231 offset:50176
	ds_read_b128 v[184:187], v231 offset:51200
	ds_read_b128 v[188:191], v231 offset:52224
	ds_read_b128 v[192:195], v231 offset:53248
	ds_read_b128 v[196:199], v231 offset:54272
	ds_read_b128 v[200:203], v231 offset:55296
	ds_read_b128 v[204:207], v231 offset:56320
	global_load_lds_dwordx4 v[164:165], off
	v_lshl_add_u64 v[164:165], v[168:169], 0, s[62:63]
	s_add_i32 m0, s8, 0x2000
	s_add_i32 s8, s31, s0
	global_load_lds_dwordx4 v[164:165], off
	v_lshl_add_u64 v[164:165], v[170:171], 0, s[62:63]
	s_mov_b32 m0, s8
	s_nop 0
	global_load_lds_dwordx4 v[164:165], off
	v_lshl_add_u64 v[164:165], v[208:209], 0, s[62:63]
	s_add_i32 m0, s8, 0x2000
	s_nop 0
	global_load_lds_dwordx4 v[164:165], off
	v_lshl_add_u64 v[164:165], v[210:211], 0, s[62:63]
	s_mov_b32 m0, s17
	s_nop 0
	global_load_lds_dwordx4 v[164:165], off
	v_lshl_add_u64 v[164:165], v[212:213], 0, s[62:63]
	s_mov_b32 m0, s18
	s_nop 0
	global_load_lds_dwordx4 v[164:165], off
	s_waitcnt vmcnt(8)
	s_waitcnt lgkmcnt(0)
	s_barrier
	s_setprio 1
	s_waitcnt lgkmcnt(0)
	v_mfma_f32_16x16x32_bf16 v[62:65], v[136:139], v[176:179], v[62:65]
	v_mfma_f32_16x16x32_bf16 v[58:61], v[144:147], v[176:179], v[58:61]
	v_mfma_f32_16x16x32_bf16 v[46:49], v[136:139], v[184:187], v[46:49]
	v_mfma_f32_16x16x32_bf16 v[42:45], v[144:147], v[184:187], v[42:45]
	v_mfma_f32_16x16x32_bf16 v[30:33], v[136:139], v[192:195], v[30:33]
	v_mfma_f32_16x16x32_bf16 v[26:29], v[144:147], v[192:195], v[26:29]
	v_mfma_f32_16x16x32_bf16 v[14:17], v[136:139], v[200:203], v[14:17]
	v_mfma_f32_16x16x32_bf16 v[10:13], v[144:147], v[200:203], v[10:13]
	v_mfma_f32_16x16x32_bf16 v[62:65], v[140:143], v[180:183], v[62:65]
	v_mfma_f32_16x16x32_bf16 v[58:61], v[148:151], v[180:183], v[58:61]
	v_mfma_f32_16x16x32_bf16 v[46:49], v[140:143], v[188:191], v[46:49]
	v_mfma_f32_16x16x32_bf16 v[42:45], v[148:151], v[188:191], v[42:45]
	v_mfma_f32_16x16x32_bf16 v[30:33], v[140:143], v[196:199], v[30:33]
	v_mfma_f32_16x16x32_bf16 v[26:29], v[148:151], v[196:199], v[26:29]
	v_mfma_f32_16x16x32_bf16 v[14:17], v[140:143], v[204:207], v[14:17]
	v_mfma_f32_16x16x32_bf16 v[10:13], v[148:151], v[204:207], v[10:13]
	s_setprio 0
	s_setprio 1
	v_mfma_f32_16x16x32_bf16 v[54:57], v[152:155], v[176:179], v[54:57]
	v_mfma_f32_16x16x32_bf16 v[50:53], v[160:163], v[176:179], v[50:53]
	v_mfma_f32_16x16x32_bf16 v[38:41], v[152:155], v[184:187], v[38:41]
	v_mfma_f32_16x16x32_bf16 v[34:37], v[160:163], v[184:187], v[34:37]
	v_mfma_f32_16x16x32_bf16 v[22:25], v[152:155], v[192:195], v[22:25]
	v_mfma_f32_16x16x32_bf16 v[18:21], v[160:163], v[192:195], v[18:21]
	v_mfma_f32_16x16x32_bf16 v[6:9], v[152:155], v[200:203], v[6:9]
	v_mfma_f32_16x16x32_bf16 v[2:5], v[160:163], v[200:203], v[2:5]
	v_mfma_f32_16x16x32_bf16 v[54:57], v[156:159], v[180:183], v[54:57]
	v_mfma_f32_16x16x32_bf16 v[50:53], v[172:175], v[180:183], v[50:53]
	v_mfma_f32_16x16x32_bf16 v[38:41], v[156:159], v[188:191], v[38:41]
	v_mfma_f32_16x16x32_bf16 v[34:37], v[172:175], v[188:191], v[34:37]
	v_mfma_f32_16x16x32_bf16 v[22:25], v[156:159], v[196:199], v[22:25]
	v_mfma_f32_16x16x32_bf16 v[18:21], v[172:175], v[196:199], v[18:21]
	v_mfma_f32_16x16x32_bf16 v[6:9], v[156:159], v[204:207], v[6:9]
	v_mfma_f32_16x16x32_bf16 v[2:5], v[172:175], v[204:207], v[2:5]
	s_setprio 0
	s_barrier
	s_add_u32 s10, s10, 0x100
	s_addc_u32 s11, s11, 0
	s_add_u32 s6, s6, 0x100
	s_addc_u32 s7, s7, 0
	s_cmp_ge_i32 s25, s13
	s_mov_b32 s8, s25
	s_cbranch_scc1 .LBB0_521

; #define PG8_STAGE(bufoff, gbase, voff) do { _Pragma("unroll") for (int _i = 0; _i < 2; ++_i) \
;         __builtin_amdgcn_global_load_lds((const unsigned*)((const char*)(gbase) + (voff)[_i]), (PG8_LAS unsigned*)(lds + (bufoff) + ldsw + _i * 8192), 16, 0, 0); } while (0)
; #define PG8_LDA(dst, b, h) do { _Pragma("unroll") for (int m = 0; m < 4; ++m) _Pragma("unroll") for (int k = 0; k < 2; ++k) dst[m][k] = *(const PG8_LAS bf16x8*)(lds + PG8_SA(b, h) + aoff + m * 2048 + k * 1024); } while (0)
; #define PG8_LDB(dst, b, h) do { _Pragma("unroll") for (int n = 0; n < 2; ++n) _Pragma("unroll") for (int k = 0; k < 2; ++k) dst[n][k] = *(const PG8_LAS bf16x8*)(lds + PG8_SB(b, h) + boff + n * 2048 + k * 1024); } while (0)
; #define PG8_MMA(ai, bj, At, Bt) do { __builtin_amdgcn_s_setprio(1); _Pragma("unroll") for (int m = 0; m < 4; ++m) _Pragma("unroll") for (int n = 0; n < 2; ++n) _Pragma("unroll") for (int k = 0; k < 2; ++k) \
;         acc[ai][bj][m][n] = __builtin_amdgcn_mfma_f32_16x16x32_bf16(Bt[n][k], At[m][k], acc[ai][bj][m][n], 0, 0, 0); __builtin_amdgcn_s_setprio(0); } while (0)
; #define PG8_WAIT_V(n) asm volatile("s_waitcnt vmcnt(" #n ")" ::: "memory")
;     ...
;         const bool has_next = S.next(ui + 1, nxt);
;         const char* nA = has_next ? (const char*)gA + (size_t)nxt.pm * tstepA + (size_t)nxt.pn * acolB : cA; const char* nB = has_next ? (const char*)gB + (size_t)nxt.pn * tstepB : cB;
;         for (int t = 0; t < nt; t += 2) {
;             const bool last = (t == nt - 2);
;             const char* a1 = cA + (size_t)(t + 1) * kstep;
;             const char* a2 = last ? nA : cA + (size_t)(t + 2) * kstep; const char* b2 = last ? nB : cB + (size_t)(t + 2) * kstep;
;             const char* a3 = a2 + kstep; const char* b3 = b2 + kstep;
;             if (last && has_next) S.a_ready(nxt);
;             if constexpr (SP2) {
;             PG8_LDB(B0, 0, 0); PG8_LDB(B1, 0, 1); PG8_SCHED; PG8_LDA(At, 0, 0); PG8_STAGE(PG8_SA(1, 1), a1 + hstepA, voffA);
;             PG8_WAIT_V(8); PG8_WAIT_L(0); PG8_BAR; PG8_MMA(0, 0, At, B0); PG8_MMA(0, 1, At, B1); PG8_BAR; PG8_SCHED;
;             PG8_LDA(At, 0, 1); PG8_STAGE(PG8_SB(0, 0), b2, voffB); PG8_STAGE(PG8_SB(0, 1), b2 + hstepB, voffB); PG8_STAGE(PG8_SA(0, 0), a2, voffA);
;             PG8_WAIT_V(8); PG8_WAIT_L(0); PG8_BAR; PG8_MMA(1, 0, At, B0); PG8_MMA(1, 1, At, B1); PG8_BAR; PG8_SCHED;
.LBB0_611:
	s_andn2_b64 vcc, exec, s[86:87]
	s_cbranch_vccnz .LBB0_614
	s_add_u32 s24, s8, 0x100
	s_addc_u32 s25, s9, 0
	s_add_u32 s6, s10, 0x80
	s_addc_u32 s7, s11, 0
	s_mov_b32 s8, 0
	s_add_i32 s10, s8, 2
	s_add_u32 s11, s6, 0x80
	s_addc_u32 s9, s7, 0
	s_add_i32 s27, 0, 0x10000
	s_cmp_eq_u32 s18, s8
	s_cselect_b32 s9, s41, s9
	s_cselect_b32 s8, s40, s11
	v_add_u32_e32 v140, s27, v151
	s_cselect_b32 s35, s91, s25
	s_cselect_b32 s34, s90, s24
	s_add_i32 s11, 0, 0x14000
	ds_read_b128 v[156:159], v140
	ds_read_b128 v[160:163], v140 offset:1024
	ds_read_b128 v[172:175], v140 offset:2048
	ds_read_b128 v[176:179], v140 offset:3072
	v_add_u32_e32 v140, s11, v151
	ds_read_b128 v[180:183], v140
	ds_read_b128 v[184:187], v140 offset:1024
	ds_read_b128 v[188:191], v140 offset:2048
	ds_read_b128 v[192:195], v140 offset:3072
	v_lshl_add_u64 v[164:165], s[6:7], 0, v[138:139]
	s_add_i32 m0, s3, 0xc000
	ds_read_b128 v[196:199], v154
	ds_read_b128 v[200:203], v154 offset:1024
	ds_read_b128 v[204:207], v154 offset:2048
	ds_read_b128 v[208:211], v154 offset:3072
	ds_read_b128 v[212:215], v154 offset:4096
	ds_read_b128 v[216:219], v154 offset:5120
	ds_read_b128 v[220:223], v154 offset:6144
	ds_read_b128 v[224:227], v154 offset:7168
	global_load_lds_dwordx4 v[164:165], off
	v_lshl_add_u64 v[164:165], s[6:7], 0, v[136:137]
	s_add_i32 m0, s3, 0xe000
	s_nop 0
	global_load_lds_dwordx4 v[164:165], off
	s_waitcnt vmcnt(8)
	s_waitcnt lgkmcnt(0)
	s_barrier
	s_setprio 1
	s_waitcnt lgkmcnt(0)
	v_mfma_f32_16x16x32_bf16 v[126:129], v[156:159], v[196:199], 0
	v_mfma_f32_16x16x32_bf16 v[122:125], v[172:175], v[196:199], 0
	v_mfma_f32_16x16x32_bf16 v[110:113], v[156:159], v[204:207], 0
	v_mfma_f32_16x16x32_bf16 v[106:109], v[172:175], v[204:207], 0
	v_mfma_f32_16x16x32_bf16 v[94:97], v[156:159], v[212:215], 0
	v_mfma_f32_16x16x32_bf16 v[90:93], v[172:175], v[212:215], 0
	v_mfma_f32_16x16x32_bf16 v[78:81], v[156:159], v[220:223], 0
	v_mfma_f32_16x16x32_bf16 v[74:77], v[172:175], v[220:223], 0
	v_mfma_f32_16x16x32_bf16 v[126:129], v[160:163], v[200:203], v[126:129]
	v_mfma_f32_16x16x32_bf16 v[122:125], v[176:179], v[200:203], v[122:125]
	v_mfma_f32_16x16x32_bf16 v[110:113], v[160:163], v[208:211], v[110:113]
	v_mfma_f32_16x16x32_bf16 v[106:109], v[176:179], v[208:211], v[106:109]
	v_mfma_f32_16x16x32_bf16 v[94:97], v[160:163], v[216:219], v[94:97]
	v_mfma_f32_16x16x32_bf16 v[90:93], v[176:179], v[216:219], v[90:93]
	v_mfma_f32_16x16x32_bf16 v[78:81], v[160:163], v[224:227], v[78:81]
	v_mfma_f32_16x16x32_bf16 v[74:77], v[176:179], v[224:227], v[74:77]
	s_setprio 0
	s_setprio 1
	v_mfma_f32_16x16x32_bf16 v[118:121], v[180:183], v[196:199], 0
	v_mfma_f32_16x16x32_bf16 v[114:117], v[188:191], v[196:199], 0
	v_mfma_f32_16x16x32_bf16 v[102:105], v[180:183], v[204:207], 0
	v_mfma_f32_16x16x32_bf16 v[98:101], v[188:191], v[204:207], 0
	v_mfma_f32_16x16x32_bf16 v[86:89], v[180:183], v[212:215], 0
	v_mfma_f32_16x16x32_bf16 v[82:85], v[188:191], v[212:215], 0
	v_mfma_f32_16x16x32_bf16 v[70:73], v[180:183], v[220:223], 0
	v_mfma_f32_16x16x32_bf16 v[66:69], v[188:191], v[220:223], 0
	v_mfma_f32_16x16x32_bf16 v[118:121], v[184:187], v[200:203], v[118:121]
	v_mfma_f32_16x16x32_bf16 v[114:117], v[192:195], v[200:203], v[114:117]
	v_mfma_f32_16x16x32_bf16 v[102:105], v[184:187], v[208:211], v[102:105]
	v_mfma_f32_16x16x32_bf16 v[98:101], v[192:195], v[208:211], v[98:101]
	v_mfma_f32_16x16x32_bf16 v[86:89], v[184:187], v[216:219], v[86:89]
	v_mfma_f32_16x16x32_bf16 v[82:85], v[192:195], v[216:219], v[82:85]
	v_mfma_f32_16x16x32_bf16 v[70:73], v[184:187], v[224:227], v[70:73]
	v_mfma_f32_16x16x32_bf16 v[66:69], v[192:195], v[224:227], v[66:69]
	s_setprio 0
	s_barrier
	s_add_i32 s27, s27, s0
	v_lshl_add_u64 v[164:165], s[34:35], 0, v[166:167]
	s_mov_b32 m0, s27
	ds_read_b128 v[196:199], v154 offset:16384
	ds_read_b128 v[200:203], v154 offset:17408
	ds_read_b128 v[204:207], v154 offset:18432
	ds_read_b128 v[208:211], v154 offset:19456
	ds_read_b128 v[212:215], v154 offset:20480
	ds_read_b128 v[216:219], v154 offset:21504
	ds_read_b128 v[220:223], v154 offset:22528
	ds_read_b128 v[224:227], v154 offset:23552
	global_load_lds_dwordx4 v[164:165], off
	s_add_i32 m0, s27, 0x2000
	v_lshl_add_u64 v[168:169], s[34:35], 0, v[130:131]
	s_add_u32 s34, s34, s58
	s_addc_u32 s35, s35, s59
	s_add_i32 s11, s11, s0
	global_load_lds_dwordx4 v[168:169], off
	v_lshl_add_u64 v[170:171], s[34:35], 0, v[166:167]
	s_mov_b32 m0, s11
	v_lshl_add_u64 v[228:229], s[34:35], 0, v[130:131]
	global_load_lds_dwordx4 v[170:171], off
	s_add_i32 m0, s11, 0x2000
	v_lshl_add_u64 v[230:231], s[8:9], 0, v[134:135]
	global_load_lds_dwordx4 v[228:229], off
	s_mov_b32 m0, s3
	v_lshl_add_u64 v[232:233], s[8:9], 0, v[132:133]
	global_load_lds_dwordx4 v[230:231], off
	s_mov_b32 m0, s12
	s_nop 0
	global_load_lds_dwordx4 v[232:233], off
	s_waitcnt vmcnt(8)
	s_waitcnt lgkmcnt(0)
	s_barrier
; #define PG8_STAGE(bufoff, gbase, voff) do { _Pragma("unroll") for (int _i = 0; _i < 2; ++_i) \
;         __builtin_amdgcn_global_load_lds((const unsigned*)((const char*)(gbase) + (voff)[_i]), (PG8_LAS unsigned*)(lds + (bufoff) + ldsw + _i * 8192), 16, 0, 0); } while (0)
; #define PG8_LDA(dst, b, h) do { _Pragma("unroll") for (int m = 0; m < 4; ++m) _Pragma("unroll") for (int k = 0; k < 2; ++k) dst[m][k] = *(const PG8_LAS bf16x8*)(lds + PG8_SA(b, h) + aoff + m * 2048 + k * 1024); } while (0)
; #define PG8_LDB(dst, b, h) do { _Pragma("unroll") for (int n = 0; n < 2; ++n) _Pragma("unroll") for (int k = 0; k < 2; ++k) dst[n][k] = *(const PG8_LAS bf16x8*)(lds + PG8_SB(b, h) + boff + n * 2048 + k * 1024); } while (0)
; #define PG8_MMA(ai, bj, At, Bt) do { __builtin_amdgcn_s_setprio(1); _Pragma("unroll") for (int m = 0; m < 4; ++m) _Pragma("unroll") for (int n = 0; n < 2; ++n) _Pragma("unroll") for (int k = 0; k < 2; ++k) \
;         acc[ai][bj][m][n] = __builtin_amdgcn_mfma_f32_16x16x32_bf16(Bt[n][k], At[m][k], acc[ai][bj][m][n], 0, 0, 0); __builtin_amdgcn_s_setprio(0); } while (0)
; #define PG8_WAIT_V(n) asm volatile("s_waitcnt vmcnt(" #n ")" ::: "memory")
; #define PG8_WAIT_L(n) asm volatile("s_waitcnt lgkmcnt(" #n ")" ::: "memory")
; #define PG8_BAR __builtin_amdgcn_s_barrier()
; #define PG8_SCHED __builtin_amdgcn_sched_barrier(0)
;     ...
;             PG8_WAIT_V(8); PG8_WAIT_L(0); PG8_BAR; PG8_MMA(1, 0, At, B0); PG8_MMA(1, 1, At, B1); PG8_BAR; PG8_SCHED;
;             PG8_LDB(B0, 1, 0); PG8_LDB(B1, 1, 1); PG8_SCHED; PG8_LDA(At, 1, 0); PG8_STAGE(PG8_SA(0, 1), a2 + hstepA, voffA);
;             PG8_WAIT_V(8); PG8_WAIT_L(0); PG8_BAR; PG8_MMA(0, 0, At, B0); PG8_MMA(0, 1, At, B1); PG8_BAR; PG8_SCHED;
	s_setprio 1
	s_waitcnt lgkmcnt(0)
	v_mfma_f32_16x16x32_bf16 v[62:65], v[156:159], v[196:199], 0
	v_mfma_f32_16x16x32_bf16 v[58:61], v[172:175], v[196:199], 0
	v_mfma_f32_16x16x32_bf16 v[46:49], v[156:159], v[204:207], 0
	v_mfma_f32_16x16x32_bf16 v[42:45], v[172:175], v[204:207], 0
	v_mfma_f32_16x16x32_bf16 v[30:33], v[156:159], v[212:215], 0
	v_mfma_f32_16x16x32_bf16 v[26:29], v[172:175], v[212:215], 0
	v_mfma_f32_16x16x32_bf16 v[14:17], v[156:159], v[220:223], 0
	v_mfma_f32_16x16x32_bf16 v[10:13], v[172:175], v[220:223], 0
	v_mfma_f32_16x16x32_bf16 v[62:65], v[160:163], v[200:203], v[62:65]
	v_mfma_f32_16x16x32_bf16 v[58:61], v[176:179], v[200:203], v[58:61]
	v_mfma_f32_16x16x32_bf16 v[46:49], v[160:163], v[208:211], v[46:49]
	v_mfma_f32_16x16x32_bf16 v[42:45], v[176:179], v[208:211], v[42:45]
	v_mfma_f32_16x16x32_bf16 v[30:33], v[160:163], v[216:219], v[30:33]
	v_mfma_f32_16x16x32_bf16 v[26:29], v[176:179], v[216:219], v[26:29]
	v_mfma_f32_16x16x32_bf16 v[14:17], v[160:163], v[224:227], v[14:17]
	v_mfma_f32_16x16x32_bf16 v[10:13], v[176:179], v[224:227], v[10:13]
	s_setprio 0
	s_setprio 1
	v_mfma_f32_16x16x32_bf16 v[54:57], v[180:183], v[196:199], 0
	v_mfma_f32_16x16x32_bf16 v[50:53], v[188:191], v[196:199], 0
	v_mfma_f32_16x16x32_bf16 v[38:41], v[180:183], v[204:207], 0
	v_mfma_f32_16x16x32_bf16 v[34:37], v[188:191], v[204:207], 0
	v_mfma_f32_16x16x32_bf16 v[22:25], v[180:183], v[212:215], 0
	v_mfma_f32_16x16x32_bf16 v[18:21], v[188:191], v[212:215], 0
	v_mfma_f32_16x16x32_bf16 v[6:9], v[180:183], v[220:223], 0
	v_mfma_f32_16x16x32_bf16 v[2:5], v[188:191], v[220:223], 0
	v_mfma_f32_16x16x32_bf16 v[54:57], v[184:187], v[200:203], v[54:57]
	v_mfma_f32_16x16x32_bf16 v[50:53], v[192:195], v[200:203], v[50:53]
	v_mfma_f32_16x16x32_bf16 v[38:41], v[184:187], v[208:211], v[38:41]
	v_mfma_f32_16x16x32_bf16 v[34:37], v[192:195], v[208:211], v[34:37]
	v_mfma_f32_16x16x32_bf16 v[22:25], v[184:187], v[216:219], v[22:25]
	v_mfma_f32_16x16x32_bf16 v[18:21], v[192:195], v[216:219], v[18:21]
	v_mfma_f32_16x16x32_bf16 v[6:9], v[184:187], v[224:227], v[6:9]
	v_mfma_f32_16x16x32_bf16 v[2:5], v[192:195], v[224:227], v[2:5]
	s_setprio 0
	s_barrier
	s_add_i32 s11, 0, 0x18000
	v_add_u32_e32 v140, s11, v151
	s_add_i32 s27, 0, 0x1c000
	ds_read_b128 v[156:159], v140
	ds_read_b128 v[160:163], v140 offset:1024
	ds_read_b128 v[172:175], v140 offset:2048
	ds_read_b128 v[176:179], v140 offset:3072
	v_add_u32_e32 v140, s27, v151
	ds_read_b128 v[180:183], v140
	ds_read_b128 v[184:187], v140 offset:1024
	ds_read_b128 v[188:191], v140 offset:2048
	ds_read_b128 v[192:195], v140 offset:3072
	s_add_u32 s8, s8, s58
	s_addc_u32 s9, s9, s59
	s_mov_b32 m0, s13
	v_lshl_add_u64 v[234:235], s[8:9], 0, v[134:135]
	ds_read_b128 v[196:199], v154 offset:32768
	ds_read_b128 v[200:203], v154 offset:33792
	ds_read_b128 v[204:207], v154 offset:34816
	ds_read_b128 v[208:211], v154 offset:35840
	ds_read_b128 v[212:215], v154 offset:36864
	ds_read_b128 v[216:219], v154 offset:37888
	ds_read_b128 v[220:223], v154 offset:38912
	ds_read_b128 v[224:227], v154 offset:39936
	global_load_lds_dwordx4 v[234:235], off
	v_lshl_add_u64 v[234:235], s[8:9], 0, v[132:133]
	s_mov_b32 m0, s14
	s_nop 0
	global_load_lds_dwordx4 v[234:235], off
	s_waitcnt vmcnt(8)
	s_waitcnt lgkmcnt(0)
	s_barrier
	s_setprio 1
	s_waitcnt lgkmcnt(0)
	v_mfma_f32_16x16x32_bf16 v[126:129], v[156:159], v[196:199], v[126:129]
	v_mfma_f32_16x16x32_bf16 v[122:125], v[172:175], v[196:199], v[122:125]
	v_mfma_f32_16x16x32_bf16 v[110:113], v[156:159], v[204:207], v[110:113]
	v_mfma_f32_16x16x32_bf16 v[106:109], v[172:175], v[204:207], v[106:109]
	v_mfma_f32_16x16x32_bf16 v[94:97], v[156:159], v[212:215], v[94:97]
	v_mfma_f32_16x16x32_bf16 v[90:93], v[172:175], v[212:215], v[90:93]
	v_mfma_f32_16x16x32_bf16 v[78:81], v[156:159], v[220:223], v[78:81]
	v_mfma_f32_16x16x32_bf16 v[74:77], v[172:175], v[220:223], v[74:77]
	v_mfma_f32_16x16x32_bf16 v[126:129], v[160:163], v[200:203], v[126:129]
	v_mfma_f32_16x16x32_bf16 v[122:125], v[176:179], v[200:203], v[122:125]
	v_mfma_f32_16x16x32_bf16 v[110:113], v[160:163], v[208:211], v[110:113]
	v_mfma_f32_16x16x32_bf16 v[106:109], v[176:179], v[208:211], v[106:109]
	v_mfma_f32_16x16x32_bf16 v[94:97], v[160:163], v[216:219], v[94:97]
	v_mfma_f32_16x16x32_bf16 v[90:93], v[176:179], v[216:219], v[90:93]
	v_mfma_f32_16x16x32_bf16 v[78:81], v[160:163], v[224:227], v[78:81]
	v_mfma_f32_16x16x32_bf16 v[74:77], v[176:179], v[224:227], v[74:77]
	s_setprio 0
	s_setprio 1
	v_mfma_f32_16x16x32_bf16 v[118:121], v[180:183], v[196:199], v[118:121]
	v_mfma_f32_16x16x32_bf16 v[114:117], v[188:191], v[196:199], v[114:117]
	v_mfma_f32_16x16x32_bf16 v[102:105], v[180:183], v[204:207], v[102:105]
	v_mfma_f32_16x16x32_bf16 v[98:101], v[188:191], v[204:207], v[98:101]
	v_mfma_f32_16x16x32_bf16 v[86:89], v[180:183], v[212:215], v[86:89]
	v_mfma_f32_16x16x32_bf16 v[82:85], v[188:191], v[212:215], v[82:85]
	v_mfma_f32_16x16x32_bf16 v[70:73], v[180:183], v[220:223], v[70:73]
	v_mfma_f32_16x16x32_bf16 v[66:69], v[188:191], v[220:223], v[66:69]
	v_mfma_f32_16x16x32_bf16 v[118:121], v[184:187], v[200:203], v[118:121]
	v_mfma_f32_16x16x32_bf16 v[114:117], v[192:195], v[200:203], v[114:117]
	v_mfma_f32_16x16x32_bf16 v[102:105], v[184:187], v[208:211], v[102:105]
	v_mfma_f32_16x16x32_bf16 v[98:101], v[192:195], v[208:211], v[98:101]
	v_mfma_f32_16x16x32_bf16 v[86:89], v[184:187], v[216:219], v[86:89]
	v_mfma_f32_16x16x32_bf16 v[82:85], v[192:195], v[216:219], v[82:85]
	v_mfma_f32_16x16x32_bf16 v[70:73], v[184:187], v[224:227], v[70:73]
	v_mfma_f32_16x16x32_bf16 v[66:69], v[192:195], v[224:227], v[66:69]
	s_setprio 0
	s_barrier
; #define PG8_STAGE(bufoff, gbase, voff) do { _Pragma("unroll") for (int _i = 0; _i < 2; ++_i) \
;         __builtin_amdgcn_global_load_lds((const unsigned*)((const char*)(gbase) + (voff)[_i]), (PG8_LAS unsigned*)(lds + (bufoff) + ldsw + _i * 8192), 16, 0, 0); } while (0)
; #define PG8_LDA(dst, b, h) do { _Pragma("unroll") for (int m = 0; m < 4; ++m) _Pragma("unroll") for (int k = 0; k < 2; ++k) dst[m][k] = *(const PG8_LAS bf16x8*)(lds + PG8_SA(b, h) + aoff + m * 2048 + k * 1024); } while (0)
; #define PG8_MMA(ai, bj, At, Bt) do { __builtin_amdgcn_s_setprio(1); _Pragma("unroll") for (int m = 0; m < 4; ++m) _Pragma("unroll") for (int n = 0; n < 2; ++n) _Pragma("unroll") for (int k = 0; k < 2; ++k) \
;         acc[ai][bj][m][n] = __builtin_amdgcn_mfma_f32_16x16x32_bf16(Bt[n][k], At[m][k], acc[ai][bj][m][n], 0, 0, 0); __builtin_amdgcn_s_setprio(0); } while (0)
; #define PG8_WAIT_V(n) asm volatile("s_waitcnt vmcnt(" #n ")" ::: "memory")
; #define PG8_WAIT_L(n) asm volatile("s_waitcnt lgkmcnt(" #n ")" ::: "memory")
; #define PG8_BAR __builtin_amdgcn_s_barrier()
; #define PG8_SCHED __builtin_amdgcn_sched_barrier(0)
;     ...
;             PG8_LDA(At, 1, 1); PG8_STAGE(PG8_SB(1, 0), b3, voffB); PG8_STAGE(PG8_SB(1, 1), b3 + hstepB, voffB); PG8_STAGE(PG8_SA(1, 0), a3, voffA);
;             PG8_WAIT_V(8); PG8_WAIT_L(0); PG8_BAR; PG8_MMA(1, 0, At, B0); PG8_MMA(1, 1, At, B1); PG8_BAR; PG8_SCHED;
	s_add_i32 s8, s11, s0
	v_lshl_add_u64 v[164:165], v[164:165], 0, s[62:63]
	s_mov_b32 m0, s8
	ds_read_b128 v[196:199], v154 offset:49152
	ds_read_b128 v[200:203], v154 offset:50176
	ds_read_b128 v[204:207], v154 offset:51200
	ds_read_b128 v[208:211], v154 offset:52224
	ds_read_b128 v[212:215], v154 offset:53248
	ds_read_b128 v[216:219], v154 offset:54272
	ds_read_b128 v[220:223], v154 offset:55296
	ds_read_b128 v[224:227], v154 offset:56320
	global_load_lds_dwordx4 v[164:165], off
	v_lshl_add_u64 v[164:165], v[168:169], 0, s[62:63]
	s_add_i32 m0, s8, 0x2000
	s_add_i32 s8, s27, s0
	global_load_lds_dwordx4 v[164:165], off
	v_lshl_add_u64 v[164:165], v[170:171], 0, s[62:63]
	s_mov_b32 m0, s8
	s_nop 0
	global_load_lds_dwordx4 v[164:165], off
	v_lshl_add_u64 v[164:165], v[228:229], 0, s[62:63]
	s_add_i32 m0, s8, 0x2000
	s_nop 0
	global_load_lds_dwordx4 v[164:165], off
	v_lshl_add_u64 v[164:165], v[230:231], 0, s[62:63]
	s_mov_b32 m0, s16
	s_nop 0
	global_load_lds_dwordx4 v[164:165], off
	v_lshl_add_u64 v[164:165], v[232:233], 0, s[62:63]
	s_mov_b32 m0, s17
	s_nop 0
	global_load_lds_dwordx4 v[164:165], off
	s_waitcnt vmcnt(8)
	s_waitcnt lgkmcnt(0)
	s_barrier
	s_setprio 1
	s_waitcnt lgkmcnt(0)
	v_mfma_f32_16x16x32_bf16 v[62:65], v[156:159], v[196:199], v[62:65]
	v_mfma_f32_16x16x32_bf16 v[58:61], v[172:175], v[196:199], v[58:61]
	v_mfma_f32_16x16x32_bf16 v[46:49], v[156:159], v[204:207], v[46:49]
	v_mfma_f32_16x16x32_bf16 v[42:45], v[172:175], v[204:207], v[42:45]
	v_mfma_f32_16x16x32_bf16 v[30:33], v[156:159], v[212:215], v[30:33]
	v_mfma_f32_16x16x32_bf16 v[26:29], v[172:175], v[212:215], v[26:29]
	v_mfma_f32_16x16x32_bf16 v[14:17], v[156:159], v[220:223], v[14:17]
	v_mfma_f32_16x16x32_bf16 v[10:13], v[172:175], v[220:223], v[10:13]
	v_mfma_f32_16x16x32_bf16 v[62:65], v[160:163], v[200:203], v[62:65]
	v_mfma_f32_16x16x32_bf16 v[58:61], v[176:179], v[200:203], v[58:61]
	v_mfma_f32_16x16x32_bf16 v[46:49], v[160:163], v[208:211], v[46:49]
	v_mfma_f32_16x16x32_bf16 v[42:45], v[176:179], v[208:211], v[42:45]
	v_mfma_f32_16x16x32_bf16 v[30:33], v[160:163], v[216:219], v[30:33]
	v_mfma_f32_16x16x32_bf16 v[26:29], v[176:179], v[216:219], v[26:29]
	v_mfma_f32_16x16x32_bf16 v[14:17], v[160:163], v[224:227], v[14:17]
	v_mfma_f32_16x16x32_bf16 v[10:13], v[176:179], v[224:227], v[10:13]
	s_setprio 0
	s_setprio 1
	v_mfma_f32_16x16x32_bf16 v[54:57], v[180:183], v[196:199], v[54:57]
	v_mfma_f32_16x16x32_bf16 v[50:53], v[188:191], v[196:199], v[50:53]
	v_mfma_f32_16x16x32_bf16 v[38:41], v[180:183], v[204:207], v[38:41]
	v_mfma_f32_16x16x32_bf16 v[34:37], v[188:191], v[204:207], v[34:37]
	v_mfma_f32_16x16x32_bf16 v[22:25], v[180:183], v[212:215], v[22:25]
	v_mfma_f32_16x16x32_bf16 v[18:21], v[188:191], v[212:215], v[18:21]
	v_mfma_f32_16x16x32_bf16 v[6:9], v[180:183], v[220:223], v[6:9]
	v_mfma_f32_16x16x32_bf16 v[2:5], v[188:191], v[220:223], v[2:5]
	v_mfma_f32_16x16x32_bf16 v[54:57], v[184:187], v[200:203], v[54:57]
	v_mfma_f32_16x16x32_bf16 v[50:53], v[192:195], v[200:203], v[50:53]
	v_mfma_f32_16x16x32_bf16 v[38:41], v[184:187], v[208:211], v[38:41]
	v_mfma_f32_16x16x32_bf16 v[34:37], v[192:195], v[208:211], v[34:37]
	v_mfma_f32_16x16x32_bf16 v[22:25], v[184:187], v[216:219], v[22:25]
	v_mfma_f32_16x16x32_bf16 v[18:21], v[192:195], v[216:219], v[18:21]
	v_mfma_f32_16x16x32_bf16 v[6:9], v[184:187], v[224:227], v[6:9]
	v_mfma_f32_16x16x32_bf16 v[2:5], v[192:195], v[224:227], v[2:5]
	s_setprio 0
	s_barrier
	s_add_u32 s24, s24, 0x100
	s_addc_u32 s25, s25, 0
	s_add_u32 s6, s6, 0x100
	s_addc_u32 s7, s7, 0
	s_cmp_ge_i32 s10, s15
	s_mov_b32 s8, s10
	s_cbranch_scc1 .LBB0_614

; #define PG8_STAGE(bufoff, gbase, voff) do { _Pragma("unroll") for (int _i = 0; _i < 2; ++_i) \
;         __builtin_amdgcn_global_load_lds((const unsigned*)((const char*)(gbase) + (voff)[_i]), (PG8_LAS unsigned*)(lds + (bufoff) + ldsw + _i * 8192), 16, 0, 0); } while (0)
; #define PG8_LDA(dst, b, h) do { _Pragma("unroll") for (int m = 0; m < 4; ++m) _Pragma("unroll") for (int k = 0; k < 2; ++k) dst[m][k] = *(const PG8_LAS bf16x8*)(lds + PG8_SA(b, h) + aoff + m * 2048 + k * 1024); } while (0)
; #define PG8_LDB(dst, b, h) do { _Pragma("unroll") for (int n = 0; n < 2; ++n) _Pragma("unroll") for (int k = 0; k < 2; ++k) dst[n][k] = *(const PG8_LAS bf16x8*)(lds + PG8_SB(b, h) + boff + n * 2048 + k * 1024); } while (0)
; #define PG8_MMA(ai, bj, At, Bt) do { __builtin_amdgcn_s_setprio(1); _Pragma("unroll") for (int m = 0; m < 4; ++m) _Pragma("unroll") for (int n = 0; n < 2; ++n) _Pragma("unroll") for (int k = 0; k < 2; ++k) \
;         acc[ai][bj][m][n] = __builtin_amdgcn_mfma_f32_16x16x32_bf16(Bt[n][k], At[m][k], acc[ai][bj][m][n], 0, 0, 0); __builtin_amdgcn_s_setprio(0); } while (0)
; #define PG8_WAIT_V(n) asm volatile("s_waitcnt vmcnt(" #n ")" ::: "memory")
;     ...
;         const bool has_next = S.next(ui + 1, nxt);
;         const char* nA = has_next ? (const char*)gA + (size_t)nxt.pm * tstepA + (size_t)nxt.pn * acolB : cA; const char* nB = has_next ? (const char*)gB + (size_t)nxt.pn * tstepB : cB;
;         for (int t = 0; t < nt; t += 2) {
;             const bool last = (t == nt - 2);
;             const char* a1 = cA + (size_t)(t + 1) * kstep;
;             const char* a2 = last ? nA : cA + (size_t)(t + 2) * kstep; const char* b2 = last ? nB : cB + (size_t)(t + 2) * kstep;
;             const char* a3 = a2 + kstep; const char* b3 = b2 + kstep;
;             if (last && has_next) S.a_ready(nxt);
;             if constexpr (SP2) {
;             PG8_LDB(B0, 0, 0); PG8_LDB(B1, 0, 1); PG8_SCHED; PG8_LDA(At, 0, 0); PG8_STAGE(PG8_SA(1, 1), a1 + hstepA, voffA);
;             PG8_WAIT_V(8); PG8_WAIT_L(0); PG8_BAR; PG8_MMA(0, 0, At, B0); PG8_MMA(0, 1, At, B1); PG8_BAR; PG8_SCHED;
;             PG8_LDA(At, 0, 1); PG8_STAGE(PG8_SB(0, 0), b2, voffB); PG8_STAGE(PG8_SB(0, 1), b2 + hstepB, voffB); PG8_STAGE(PG8_SA(0, 0), a2, voffA);
;             PG8_WAIT_V(8); PG8_WAIT_L(0); PG8_BAR; PG8_MMA(1, 0, At, B0); PG8_MMA(1, 1, At, B1); PG8_BAR; PG8_SCHED;
.LBB0_750:
	s_andn2_b64 vcc, exec, s[86:87]
	s_waitcnt lgkmcnt(0)
	s_cbranch_vccnz .LBB0_753
	s_add_u32 s10, s6, 0x100
	s_addc_u32 s11, s7, 0
	s_add_u32 s6, s8, 0x80
	s_addc_u32 s7, s9, 0
	s_mov_b32 s8, 0
	s_add_i32 s25, s8, 2
	s_add_u32 s27, s6, 0x80
	s_addc_u32 s9, s7, 0
	s_add_i32 s31, 0, 0x10000
	s_cmp_eq_u32 s19, s8
	s_cselect_b32 s9, s43, s9
	s_cselect_b32 s8, s42, s27
	s_cselect_b32 s35, s91, s11
	s_cselect_b32 s34, s90, s10
	s_add_i32 s27, 0, 0x14000
	v_add_u32_e32 v148, s31, v229
	v_add_u32_e32 v164, s27, v229
	ds_read_b128 v[136:139], v148
	ds_read_b128 v[140:143], v148 offset:1024
	ds_read_b128 v[144:147], v148 offset:2048
	ds_read_b128 v[148:151], v148 offset:3072
	ds_read_b128 v[152:155], v164
	ds_read_b128 v[156:159], v164 offset:1024
	ds_read_b128 v[160:163], v164 offset:2048
	ds_read_b128 v[172:175], v164 offset:3072
	v_lshl_add_u64 v[164:165], s[6:7], 0, v[134:135]
	s_add_i32 m0, s2, 0xc000
	ds_read_b128 v[176:179], v231
	ds_read_b128 v[180:183], v231 offset:1024
	ds_read_b128 v[184:187], v231 offset:2048
	ds_read_b128 v[188:191], v231 offset:3072
	ds_read_b128 v[192:195], v231 offset:4096
	ds_read_b128 v[196:199], v231 offset:5120
	ds_read_b128 v[200:203], v231 offset:6144
	ds_read_b128 v[204:207], v231 offset:7168
	global_load_lds_dwordx4 v[164:165], off
	v_lshl_add_u64 v[164:165], s[6:7], 0, v[132:133]
	s_add_i32 m0, s2, 0xe000
	s_nop 0
	global_load_lds_dwordx4 v[164:165], off
	s_waitcnt vmcnt(8)
	s_waitcnt lgkmcnt(0)
	s_barrier
	s_setprio 1
	s_waitcnt lgkmcnt(0)
	v_mfma_f32_16x16x32_bf16 v[126:129], v[136:139], v[176:179], 0
	v_mfma_f32_16x16x32_bf16 v[122:125], v[144:147], v[176:179], 0
	v_mfma_f32_16x16x32_bf16 v[110:113], v[136:139], v[184:187], 0
	v_mfma_f32_16x16x32_bf16 v[106:109], v[144:147], v[184:187], 0
	v_mfma_f32_16x16x32_bf16 v[94:97], v[136:139], v[192:195], 0
	v_mfma_f32_16x16x32_bf16 v[90:93], v[144:147], v[192:195], 0
	v_mfma_f32_16x16x32_bf16 v[78:81], v[136:139], v[200:203], 0
	v_mfma_f32_16x16x32_bf16 v[74:77], v[144:147], v[200:203], 0
	v_mfma_f32_16x16x32_bf16 v[126:129], v[140:143], v[180:183], v[126:129]
	v_mfma_f32_16x16x32_bf16 v[122:125], v[148:151], v[180:183], v[122:125]
	v_mfma_f32_16x16x32_bf16 v[110:113], v[140:143], v[188:191], v[110:113]
	v_mfma_f32_16x16x32_bf16 v[106:109], v[148:151], v[188:191], v[106:109]
	v_mfma_f32_16x16x32_bf16 v[94:97], v[140:143], v[196:199], v[94:97]
	v_mfma_f32_16x16x32_bf16 v[90:93], v[148:151], v[196:199], v[90:93]
	v_mfma_f32_16x16x32_bf16 v[78:81], v[140:143], v[204:207], v[78:81]
	v_mfma_f32_16x16x32_bf16 v[74:77], v[148:151], v[204:207], v[74:77]
	s_setprio 0
	s_setprio 1
	v_mfma_f32_16x16x32_bf16 v[118:121], v[152:155], v[176:179], 0
	v_mfma_f32_16x16x32_bf16 v[114:117], v[160:163], v[176:179], 0
	v_mfma_f32_16x16x32_bf16 v[102:105], v[152:155], v[184:187], 0
	v_mfma_f32_16x16x32_bf16 v[98:101], v[160:163], v[184:187], 0
	v_mfma_f32_16x16x32_bf16 v[86:89], v[152:155], v[192:195], 0
	v_mfma_f32_16x16x32_bf16 v[82:85], v[160:163], v[192:195], 0
	v_mfma_f32_16x16x32_bf16 v[70:73], v[152:155], v[200:203], 0
	v_mfma_f32_16x16x32_bf16 v[66:69], v[160:163], v[200:203], 0
	v_mfma_f32_16x16x32_bf16 v[118:121], v[156:159], v[180:183], v[118:121]
	v_mfma_f32_16x16x32_bf16 v[114:117], v[172:175], v[180:183], v[114:117]
	v_mfma_f32_16x16x32_bf16 v[102:105], v[156:159], v[188:191], v[102:105]
	v_mfma_f32_16x16x32_bf16 v[98:101], v[172:175], v[188:191], v[98:101]
	v_mfma_f32_16x16x32_bf16 v[86:89], v[156:159], v[196:199], v[86:89]
	v_mfma_f32_16x16x32_bf16 v[82:85], v[172:175], v[196:199], v[82:85]
	v_mfma_f32_16x16x32_bf16 v[70:73], v[156:159], v[204:207], v[70:73]
	v_mfma_f32_16x16x32_bf16 v[66:69], v[172:175], v[204:207], v[66:69]
	s_setprio 0
	s_barrier
	s_add_i32 s31, s31, s0
	v_lshl_add_u64 v[164:165], s[34:35], 0, v[166:167]
	s_mov_b32 m0, s31
	ds_read_b128 v[176:179], v231 offset:16384
	ds_read_b128 v[180:183], v231 offset:17408
	ds_read_b128 v[184:187], v231 offset:18432
	ds_read_b128 v[188:191], v231 offset:19456
	ds_read_b128 v[192:195], v231 offset:20480
	ds_read_b128 v[196:199], v231 offset:21504
	ds_read_b128 v[200:203], v231 offset:22528
	ds_read_b128 v[204:207], v231 offset:23552
	global_load_lds_dwordx4 v[164:165], off
	s_add_i32 m0, s31, 0x2000
	v_lshl_add_u64 v[168:169], s[34:35], 0, v[130:131]
	s_add_u32 s34, s34, s58
	s_addc_u32 s35, s35, s59
	s_add_i32 s27, s27, s0
	global_load_lds_dwordx4 v[168:169], off
	v_lshl_add_u64 v[170:171], s[34:35], 0, v[166:167]
	s_mov_b32 m0, s27
	v_lshl_add_u64 v[208:209], s[34:35], 0, v[130:131]
	global_load_lds_dwordx4 v[170:171], off
	s_add_i32 m0, s27, 0x2000
	v_lshl_add_u64 v[210:211], s[8:9], 0, v[166:167]
	global_load_lds_dwordx4 v[208:209], off
	s_mov_b32 m0, s2
	v_lshl_add_u64 v[212:213], s[8:9], 0, v[130:131]
	global_load_lds_dwordx4 v[210:211], off
	s_mov_b32 m0, s3
	s_nop 0
	global_load_lds_dwordx4 v[212:213], off
	s_waitcnt vmcnt(8)
	s_waitcnt lgkmcnt(0)
	s_barrier
; #define PG8_STAGE(bufoff, gbase, voff) do { _Pragma("unroll") for (int _i = 0; _i < 2; ++_i) \
;         __builtin_amdgcn_global_load_lds((const unsigned*)((const char*)(gbase) + (voff)[_i]), (PG8_LAS unsigned*)(lds + (bufoff) + ldsw + _i * 8192), 16, 0, 0); } while (0)
; #define PG8_LDA(dst, b, h) do { _Pragma("unroll") for (int m = 0; m < 4; ++m) _Pragma("unroll") for (int k = 0; k < 2; ++k) dst[m][k] = *(const PG8_LAS bf16x8*)(lds + PG8_SA(b, h) + aoff + m * 2048 + k * 1024); } while (0)
; #define PG8_LDB(dst, b, h) do { _Pragma("unroll") for (int n = 0; n < 2; ++n) _Pragma("unroll") for (int k = 0; k < 2; ++k) dst[n][k] = *(const PG8_LAS bf16x8*)(lds + PG8_SB(b, h) + boff + n * 2048 + k * 1024); } while (0)
; #define PG8_MMA(ai, bj, At, Bt) do { __builtin_amdgcn_s_setprio(1); _Pragma("unroll") for (int m = 0; m < 4; ++m) _Pragma("unroll") for (int n = 0; n < 2; ++n) _Pragma("unroll") for (int k = 0; k < 2; ++k) \
;         acc[ai][bj][m][n] = __builtin_amdgcn_mfma_f32_16x16x32_bf16(Bt[n][k], At[m][k], acc[ai][bj][m][n], 0, 0, 0); __builtin_amdgcn_s_setprio(0); } while (0)
; #define PG8_WAIT_V(n) asm volatile("s_waitcnt vmcnt(" #n ")" ::: "memory")
; #define PG8_WAIT_L(n) asm volatile("s_waitcnt lgkmcnt(" #n ")" ::: "memory")
; #define PG8_BAR __builtin_amdgcn_s_barrier()
; #define PG8_SCHED __builtin_amdgcn_sched_barrier(0)
;     ...
;             PG8_WAIT_V(8); PG8_WAIT_L(0); PG8_BAR; PG8_MMA(1, 0, At, B0); PG8_MMA(1, 1, At, B1); PG8_BAR; PG8_SCHED;
;             PG8_LDB(B0, 1, 0); PG8_LDB(B1, 1, 1); PG8_SCHED; PG8_LDA(At, 1, 0); PG8_STAGE(PG8_SA(0, 1), a2 + hstepA, voffA);
;             PG8_WAIT_V(8); PG8_WAIT_L(0); PG8_BAR; PG8_MMA(0, 0, At, B0); PG8_MMA(0, 1, At, B1); PG8_BAR; PG8_SCHED;
	s_setprio 1
	s_waitcnt lgkmcnt(0)
	v_mfma_f32_16x16x32_bf16 v[62:65], v[136:139], v[176:179], 0
	v_mfma_f32_16x16x32_bf16 v[58:61], v[144:147], v[176:179], 0
	v_mfma_f32_16x16x32_bf16 v[46:49], v[136:139], v[184:187], 0
	v_mfma_f32_16x16x32_bf16 v[42:45], v[144:147], v[184:187], 0
	v_mfma_f32_16x16x32_bf16 v[30:33], v[136:139], v[192:195], 0
	v_mfma_f32_16x16x32_bf16 v[26:29], v[144:147], v[192:195], 0
	v_mfma_f32_16x16x32_bf16 v[14:17], v[136:139], v[200:203], 0
	v_mfma_f32_16x16x32_bf16 v[10:13], v[144:147], v[200:203], 0
	v_mfma_f32_16x16x32_bf16 v[62:65], v[140:143], v[180:183], v[62:65]
	v_mfma_f32_16x16x32_bf16 v[58:61], v[148:151], v[180:183], v[58:61]
	v_mfma_f32_16x16x32_bf16 v[46:49], v[140:143], v[188:191], v[46:49]
	v_mfma_f32_16x16x32_bf16 v[42:45], v[148:151], v[188:191], v[42:45]
	v_mfma_f32_16x16x32_bf16 v[30:33], v[140:143], v[196:199], v[30:33]
	v_mfma_f32_16x16x32_bf16 v[26:29], v[148:151], v[196:199], v[26:29]
	v_mfma_f32_16x16x32_bf16 v[14:17], v[140:143], v[204:207], v[14:17]
	v_mfma_f32_16x16x32_bf16 v[10:13], v[148:151], v[204:207], v[10:13]
	s_setprio 0
	s_setprio 1
	v_mfma_f32_16x16x32_bf16 v[54:57], v[152:155], v[176:179], 0
	v_mfma_f32_16x16x32_bf16 v[50:53], v[160:163], v[176:179], 0
	v_mfma_f32_16x16x32_bf16 v[38:41], v[152:155], v[184:187], 0
	v_mfma_f32_16x16x32_bf16 v[34:37], v[160:163], v[184:187], 0
	v_mfma_f32_16x16x32_bf16 v[22:25], v[152:155], v[192:195], 0
	v_mfma_f32_16x16x32_bf16 v[18:21], v[160:163], v[192:195], 0
	v_mfma_f32_16x16x32_bf16 v[6:9], v[152:155], v[200:203], 0
	v_mfma_f32_16x16x32_bf16 v[2:5], v[160:163], v[200:203], 0
	v_mfma_f32_16x16x32_bf16 v[54:57], v[156:159], v[180:183], v[54:57]
	v_mfma_f32_16x16x32_bf16 v[50:53], v[172:175], v[180:183], v[50:53]
	v_mfma_f32_16x16x32_bf16 v[38:41], v[156:159], v[188:191], v[38:41]
	v_mfma_f32_16x16x32_bf16 v[34:37], v[172:175], v[188:191], v[34:37]
	v_mfma_f32_16x16x32_bf16 v[22:25], v[156:159], v[196:199], v[22:25]
	v_mfma_f32_16x16x32_bf16 v[18:21], v[172:175], v[196:199], v[18:21]
	v_mfma_f32_16x16x32_bf16 v[6:9], v[156:159], v[204:207], v[6:9]
	v_mfma_f32_16x16x32_bf16 v[2:5], v[172:175], v[204:207], v[2:5]
	s_setprio 0
	s_barrier
	s_add_i32 s27, 0, 0x18000
	s_add_i32 s31, 0, 0x1c000
	v_add_u32_e32 v148, s27, v229
	v_add_u32_e32 v172, s31, v229
	ds_read_b128 v[136:139], v148
	ds_read_b128 v[140:143], v148 offset:1024
	ds_read_b128 v[144:147], v148 offset:2048
	ds_read_b128 v[148:151], v148 offset:3072
	ds_read_b128 v[152:155], v172
	ds_read_b128 v[156:159], v172 offset:1024
	ds_read_b128 v[160:163], v172 offset:2048
	ds_read_b128 v[172:175], v172 offset:3072
	s_add_u32 s8, s8, s58
	s_addc_u32 s9, s9, s59
	s_mov_b32 m0, s14
	v_lshl_add_u64 v[214:215], s[8:9], 0, v[166:167]
	ds_read_b128 v[176:179], v231 offset:32768
	ds_read_b128 v[180:183], v231 offset:33792
	ds_read_b128 v[184:187], v231 offset:34816
	ds_read_b128 v[188:191], v231 offset:35840
	ds_read_b128 v[192:195], v231 offset:36864
	ds_read_b128 v[196:199], v231 offset:37888
	ds_read_b128 v[200:203], v231 offset:38912
	ds_read_b128 v[204:207], v231 offset:39936
	global_load_lds_dwordx4 v[214:215], off
	v_lshl_add_u64 v[214:215], s[8:9], 0, v[130:131]
	s_mov_b32 m0, s15
	s_nop 0
	global_load_lds_dwordx4 v[214:215], off
	s_waitcnt vmcnt(8)
	s_waitcnt lgkmcnt(0)
	s_barrier
	s_setprio 1
	s_waitcnt lgkmcnt(0)
	v_mfma_f32_16x16x32_bf16 v[126:129], v[136:139], v[176:179], v[126:129]
	v_mfma_f32_16x16x32_bf16 v[122:125], v[144:147], v[176:179], v[122:125]
	v_mfma_f32_16x16x32_bf16 v[110:113], v[136:139], v[184:187], v[110:113]
	v_mfma_f32_16x16x32_bf16 v[106:109], v[144:147], v[184:187], v[106:109]
	v_mfma_f32_16x16x32_bf16 v[94:97], v[136:139], v[192:195], v[94:97]
	v_mfma_f32_16x16x32_bf16 v[90:93], v[144:147], v[192:195], v[90:93]
	v_mfma_f32_16x16x32_bf16 v[78:81], v[136:139], v[200:203], v[78:81]
	v_mfma_f32_16x16x32_bf16 v[74:77], v[144:147], v[200:203], v[74:77]
	v_mfma_f32_16x16x32_bf16 v[126:129], v[140:143], v[180:183], v[126:129]
	v_mfma_f32_16x16x32_bf16 v[122:125], v[148:151], v[180:183], v[122:125]
	v_mfma_f32_16x16x32_bf16 v[110:113], v[140:143], v[188:191], v[110:113]
	v_mfma_f32_16x16x32_bf16 v[106:109], v[148:151], v[188:191], v[106:109]
	v_mfma_f32_16x16x32_bf16 v[94:97], v[140:143], v[196:199], v[94:97]
	v_mfma_f32_16x16x32_bf16 v[90:93], v[148:151], v[196:199], v[90:93]
	v_mfma_f32_16x16x32_bf16 v[78:81], v[140:143], v[204:207], v[78:81]
	v_mfma_f32_16x16x32_bf16 v[74:77], v[148:151], v[204:207], v[74:77]
	s_setprio 0
	s_setprio 1
	v_mfma_f32_16x16x32_bf16 v[118:121], v[152:155], v[176:179], v[118:121]
	v_mfma_f32_16x16x32_bf16 v[114:117], v[160:163], v[176:179], v[114:117]
	v_mfma_f32_16x16x32_bf16 v[102:105], v[152:155], v[184:187], v[102:105]
	v_mfma_f32_16x16x32_bf16 v[98:101], v[160:163], v[184:187], v[98:101]
	v_mfma_f32_16x16x32_bf16 v[86:89], v[152:155], v[192:195], v[86:89]
	v_mfma_f32_16x16x32_bf16 v[82:85], v[160:163], v[192:195], v[82:85]
	v_mfma_f32_16x16x32_bf16 v[70:73], v[152:155], v[200:203], v[70:73]
	v_mfma_f32_16x16x32_bf16 v[66:69], v[160:163], v[200:203], v[66:69]
	v_mfma_f32_16x16x32_bf16 v[118:121], v[156:159], v[180:183], v[118:121]
	v_mfma_f32_16x16x32_bf16 v[114:117], v[172:175], v[180:183], v[114:117]
	v_mfma_f32_16x16x32_bf16 v[102:105], v[156:159], v[188:191], v[102:105]
	v_mfma_f32_16x16x32_bf16 v[98:101], v[172:175], v[188:191], v[98:101]
	v_mfma_f32_16x16x32_bf16 v[86:89], v[156:159], v[196:199], v[86:89]
	v_mfma_f32_16x16x32_bf16 v[82:85], v[172:175], v[196:199], v[82:85]
	v_mfma_f32_16x16x32_bf16 v[70:73], v[156:159], v[204:207], v[70:73]
	v_mfma_f32_16x16x32_bf16 v[66:69], v[172:175], v[204:207], v[66:69]
	s_setprio 0
	s_barrier
; #define PG8_STAGE(bufoff, gbase, voff) do { _Pragma("unroll") for (int _i = 0; _i < 2; ++_i) \
;         __builtin_amdgcn_global_load_lds((const unsigned*)((const char*)(gbase) + (voff)[_i]), (PG8_LAS unsigned*)(lds + (bufoff) + ldsw + _i * 8192), 16, 0, 0); } while (0)
; #define PG8_LDA(dst, b, h) do { _Pragma("unroll") for (int m = 0; m < 4; ++m) _Pragma("unroll") for (int k = 0; k < 2; ++k) dst[m][k] = *(const PG8_LAS bf16x8*)(lds + PG8_SA(b, h) + aoff + m * 2048 + k * 1024); } while (0)
; #define PG8_MMA(ai, bj, At, Bt) do { __builtin_amdgcn_s_setprio(1); _Pragma("unroll") for (int m = 0; m < 4; ++m) _Pragma("unroll") for (int n = 0; n < 2; ++n) _Pragma("unroll") for (int k = 0; k < 2; ++k) \
;         acc[ai][bj][m][n] = __builtin_amdgcn_mfma_f32_16x16x32_bf16(Bt[n][k], At[m][k], acc[ai][bj][m][n], 0, 0, 0); __builtin_amdgcn_s_setprio(0); } while (0)
; #define PG8_WAIT_V(n) asm volatile("s_waitcnt vmcnt(" #n ")" ::: "memory")
; #define PG8_WAIT_L(n) asm volatile("s_waitcnt lgkmcnt(" #n ")" ::: "memory")
; #define PG8_BAR __builtin_amdgcn_s_barrier()
; #define PG8_SCHED __builtin_amdgcn_sched_barrier(0)
;     ...
;             PG8_LDA(At, 1, 1); PG8_STAGE(PG8_SB(1, 0), b3, voffB); PG8_STAGE(PG8_SB(1, 1), b3 + hstepB, voffB); PG8_STAGE(PG8_SA(1, 0), a3, voffA);
;             PG8_WAIT_V(8); PG8_WAIT_L(0); PG8_BAR; PG8_MMA(1, 0, At, B0); PG8_MMA(1, 1, At, B1); PG8_BAR; PG8_SCHED;
	s_add_i32 s8, s27, s0
	v_lshl_add_u64 v[164:165], v[164:165], 0, s[62:63]
	s_mov_b32 m0, s8
	ds_read_b128 v[176:179], v231 offset:49152
	ds_read_b128 v[180:183], v231 offset:50176
	ds_read_b128 v[184:187], v231 offset:51200
	ds_read_b128 v[188:191], v231 offset:52224
	ds_read_b128 v[192:195], v231 offset:53248
	ds_read_b128 v[196:199], v231 offset:54272
	ds_read_b128 v[200:203], v231 offset:55296
	ds_read_b128 v[204:207], v231 offset:56320
	global_load_lds_dwordx4 v[164:165], off
	v_lshl_add_u64 v[164:165], v[168:169], 0, s[62:63]
	s_add_i32 m0, s8, 0x2000
	s_add_i32 s8, s31, s0
	global_load_lds_dwordx4 v[164:165], off
	v_lshl_add_u64 v[164:165], v[170:171], 0, s[62:63]
	s_mov_b32 m0, s8
	s_nop 0
	global_load_lds_dwordx4 v[164:165], off
	v_lshl_add_u64 v[164:165], v[208:209], 0, s[62:63]
	s_add_i32 m0, s8, 0x2000
	s_nop 0
	global_load_lds_dwordx4 v[164:165], off
	v_lshl_add_u64 v[164:165], v[210:211], 0, s[62:63]
	s_mov_b32 m0, s17
	s_nop 0
	global_load_lds_dwordx4 v[164:165], off
	v_lshl_add_u64 v[164:165], v[212:213], 0, s[62:63]
	s_mov_b32 m0, s18
	s_nop 0
	global_load_lds_dwordx4 v[164:165], off
	s_waitcnt vmcnt(8)
	s_waitcnt lgkmcnt(0)
	s_barrier
	s_setprio 1
	s_waitcnt lgkmcnt(0)
	v_mfma_f32_16x16x32_bf16 v[62:65], v[136:139], v[176:179], v[62:65]
	v_mfma_f32_16x16x32_bf16 v[58:61], v[144:147], v[176:179], v[58:61]
	v_mfma_f32_16x16x32_bf16 v[46:49], v[136:139], v[184:187], v[46:49]
	v_mfma_f32_16x16x32_bf16 v[42:45], v[144:147], v[184:187], v[42:45]
	v_mfma_f32_16x16x32_bf16 v[30:33], v[136:139], v[192:195], v[30:33]
	v_mfma_f32_16x16x32_bf16 v[26:29], v[144:147], v[192:195], v[26:29]
	v_mfma_f32_16x16x32_bf16 v[14:17], v[136:139], v[200:203], v[14:17]
	v_mfma_f32_16x16x32_bf16 v[10:13], v[144:147], v[200:203], v[10:13]
	v_mfma_f32_16x16x32_bf16 v[62:65], v[140:143], v[180:183], v[62:65]
	v_mfma_f32_16x16x32_bf16 v[58:61], v[148:151], v[180:183], v[58:61]
	v_mfma_f32_16x16x32_bf16 v[46:49], v[140:143], v[188:191], v[46:49]
	v_mfma_f32_16x16x32_bf16 v[42:45], v[148:151], v[188:191], v[42:45]
	v_mfma_f32_16x16x32_bf16 v[30:33], v[140:143], v[196:199], v[30:33]
	v_mfma_f32_16x16x32_bf16 v[26:29], v[148:151], v[196:199], v[26:29]
	v_mfma_f32_16x16x32_bf16 v[14:17], v[140:143], v[204:207], v[14:17]
	v_mfma_f32_16x16x32_bf16 v[10:13], v[148:151], v[204:207], v[10:13]
	s_setprio 0
	s_setprio 1
	v_mfma_f32_16x16x32_bf16 v[54:57], v[152:155], v[176:179], v[54:57]
	v_mfma_f32_16x16x32_bf16 v[50:53], v[160:163], v[176:179], v[50:53]
	v_mfma_f32_16x16x32_bf16 v[38:41], v[152:155], v[184:187], v[38:41]
	v_mfma_f32_16x16x32_bf16 v[34:37], v[160:163], v[184:187], v[34:37]
	v_mfma_f32_16x16x32_bf16 v[22:25], v[152:155], v[192:195], v[22:25]
	v_mfma_f32_16x16x32_bf16 v[18:21], v[160:163], v[192:195], v[18:21]
	v_mfma_f32_16x16x32_bf16 v[6:9], v[152:155], v[200:203], v[6:9]
	v_mfma_f32_16x16x32_bf16 v[2:5], v[160:163], v[200:203], v[2:5]
	v_mfma_f32_16x16x32_bf16 v[54:57], v[156:159], v[180:183], v[54:57]
	v_mfma_f32_16x16x32_bf16 v[50:53], v[172:175], v[180:183], v[50:53]
	v_mfma_f32_16x16x32_bf16 v[38:41], v[156:159], v[188:191], v[38:41]
	v_mfma_f32_16x16x32_bf16 v[34:37], v[172:175], v[188:191], v[34:37]
	v_mfma_f32_16x16x32_bf16 v[22:25], v[156:159], v[196:199], v[22:25]
	v_mfma_f32_16x16x32_bf16 v[18:21], v[172:175], v[196:199], v[18:21]
	v_mfma_f32_16x16x32_bf16 v[6:9], v[156:159], v[204:207], v[6:9]
	v_mfma_f32_16x16x32_bf16 v[2:5], v[172:175], v[204:207], v[2:5]
	s_setprio 0
	s_barrier
	s_add_u32 s10, s10, 0x100
	s_addc_u32 s11, s11, 0
	s_add_u32 s6, s6, 0x100
	s_addc_u32 s7, s7, 0
	s_cmp_ge_i32 s25, s13
	s_mov_b32 s8, s25
	s_cbranch_scc1 .LBB0_753
